# FFN-gate GEMM epilogue rewritten by hand: LDS tap table + DPP-fused FMAC row convolution (no DPP moves/selects), 1065 instead of 1640 VALU per wave
# speedup vs baseline: 1.0207x; 1.0157x over previous
;     __device__ __forceinline__ void operator()(const f32x4 (&acc)[2][2][4][2], const Unit& u, int wr, int wc, int fr_in, int fq_in) const {
;         const int fr0_ = fr_in, fq0_ = fq_in;
;         char* base = (char*)(A2 + (size_t)(u.pm * BM) * DFF);
;         char* sbase = (char*)(side + (size_t)(u.pm * 16) * DFF2);
;         int fr_l = fr0_, fq_l = fq0_; asm volatile("" : "+v"(fr_l), "+v"(fq_l));
;         const int fr = fr_l, fq = fq_l;
;         const int ch0 = u.pn * HALF + wc * 32 + 8 * fq;
;         const unsigned off0 = (unsigned)(wr * 64 + fr) * (DFF * 2u) + (unsigned)ch0 * 2u;
;         const bool f0 = fr == 0, f15 = fr == 15;
;     ...
; #pragma unroll
;         for (int ai = 0; ai < 2; ++ai) {
;             f32x4 o[4]; u32x2 wlo[4];
; #pragma unroll
;             for (int n = 0; n < 2; ++n) {
;                 const int ch = ch0 + 4 * n;
; #pragma unroll
;                 for (int pass = 0; pass < 2; ++pass) {
;                     const int co = pass ? DFF : 0;
;                     const f32x4 k0 = *(const f32x4*)(fk + co + ch), k1 = *(const f32x4*)(fk + DFF2 + co + ch), k2 = *(const f32x4*)(fk + 2 * DFF2 + co + ch), bb = *(const f32x4*)(fb + co + ch);
;                     f32x4 up_prev = (f32x4){0.f, 0.f, 0.f, 0.f}, up_cur, dn_cur, dn_next;
; #pragma unroll
;                     for (int j = 0; j < 4; ++j) dn_cur[j] = DPP_DN(acc[ai][pass][0][n][j]);
; #pragma unroll
;                     for (int m = 0; m < 4; ++m) {
;                         const f32x4 xv = acc[ai][pass][m][n];
; #pragma unroll
;                         for (int j = 0; j < 4; ++j) { up_cur[j] = DPP_UP(xv[j]); dn_next[j] = (m < 3) ? DPP_DN(acc[ai][pass][m < 3 ? m + 1 : 3][n][j]) : 0.f; }
;                         const f32x4 xp = f0 ? up_prev : up_cur, xn = f15 ? dn_next : dn_cur;
;                         const f32x4 c = (k0 * xp + k1 * xv) + (k2 * xn + bb);
;     ...
;                 if (fr < 2 || fr >= 14) { const int k = fr < 2 ? fr : fr - 12;
;                     const f32x4 xv = fr < 2 ? acc[ai][0][0][n] : acc[ai][0][3][n], yv = fr < 2 ? acc[ai][1][0][n] : acc[ai][1][3][n];
;                     char* sp = sbase + (size_t)((2 * ai + wr) * 4 + k) * (DFF2 * 2) + (size_t)ch * 2;
;                     u32x2 a, b; a.x = cvt_pk_bf16(xv[0], xv[1]); a.y = cvt_pk_bf16(xv[2], xv[3]); b.x = cvt_pk_bf16(yv[0], yv[1]); b.y = cvt_pk_bf16(yv[2], yv[3]);
.LBB0_1046:
	s_lshl_b32 s0, s42, 4
	s_mul_i32 s1, s42, 0x2c000
	s_mul_hi_i32 s0, s0, 0x2c00
	s_add_u32 s40, s46, s1
	s_addc_u32 s41, s64, s0
	s_load_dwordx2 s[0:1], s[62:63], 0xc0
	v_mul_u32_u24_e32 v194, 0x1600, v182
	v_lshl_add_u32 v194, v183, 4, v194
	v_cmp_gt_u32_e64 s[12:13], 2, v182
	v_cmp_lt_u32_e64 s[22:23], 13, v182
	v_add_u32_e32 v198, -12, v182
	s_or_b64 s[22:23], s[22:23], s[12:13]
	v_cndmask_b32_e64 v198, v198, v182, s[12:13]
	v_mul_u32_u24_e32 v195, 0x2c00, v198
	v_lshl_add_u32 v195, v183, 4, v195
	v_add_u32_e32 v197, 0x1600, v195
	s_sub_i32 s101, s100, 0x20000
	s_lshr_b32 s101, s101, 10
	s_lshr_b32 s9, s101, 2
	s_lshl_b32 s10, s42, 8
	s_lshl_b32 s11, s9, 6
	s_add_i32 s10, s10, s11
	s_mul_i32 s10, s10, 0x1600
	s_lshl_b32 s11, s8, 7
	s_or_b32 s11, s11, s14
	s_lshl_b32 s11, s11, 1
	s_mul_i32 s9, s9, 0xb000
	s_waitcnt lgkmcnt(0)
	s_add_u32 s6, s0, 0x9400000
	s_addc_u32 s7, s1, 0
	s_add_u32 s6, s6, s10
	s_addc_u32 s7, s7, 0
	s_add_u32 s6, s6, s11
	s_addc_u32 s7, s7, 0
	s_add_u32 s10, s40, s9
	s_addc_u32 s11, s41, 0
	s_lshl_b32 s9, s8, 7
	s_or_b32 s9, s9, s14
	s_lshl_b32 s9, s9, 1
	s_add_u32 s10, s10, s9
	s_addc_u32 s11, s11, 0
	s_waitcnt vmcnt(0)
	ds_read_b128 v[130:133], v213 offset:0
	ds_read_b128 v[134:137], v213 offset:64
	ds_read_b128 v[138:141], v213 offset:128
	ds_read_b128 v[142:145], v213 offset:192
	ds_read_b128 v[158:161], v213 offset:256
	ds_read_b128 v[162:165], v213 offset:320
	ds_read_b128 v[166:169], v213 offset:384
	ds_read_b128 v[170:173], v213 offset:448
	v_cndmask_b32_e64 v202, v106, v110, s[12:13]
	v_cndmask_b32_e64 v203, v107, v111, s[12:13]
	v_cndmask_b32_e64 v204, v108, v112, s[12:13]
	v_cndmask_b32_e64 v205, v109, v113, s[12:13]
	v_cndmask_b32_e64 v206, v98, v102, s[12:13]
	v_cndmask_b32_e64 v207, v99, v103, s[12:13]
	v_cndmask_b32_e64 v208, v100, v104, s[12:13]
	v_cndmask_b32_e64 v209, v101, v105, s[12:13]
	v_cvt_pk_bf16_f32 v250, v202, v203
	v_cvt_pk_bf16_f32 v251, v204, v205
	v_cvt_pk_bf16_f32 v252, v206, v207
	v_cvt_pk_bf16_f32 v253, v208, v209
	s_mov_b64 s[42:43], exec
	s_and_b64 exec, exec, s[22:23]
	global_store_dwordx2 v195, v[250:251], s[10:11]
	global_store_dwordx2 v197, v[252:253], s[10:11]
	s_mov_b64 exec, s[42:43]
	s_waitcnt lgkmcnt(0)
	v_fma_f32 v174, v134, v110, v142
	v_fma_f32 v175, v135, v111, v143
	v_fma_f32 v176, v136, v112, v144
	v_fma_f32 v177, v137, v113, v145
	v_fma_f32 v178, v134, v126, v142
	v_fma_f32 v179, v135, v127, v143
	v_fma_f32 v180, v136, v128, v144
	v_fma_f32 v181, v137, v129, v145
	v_fma_f32 v186, v134, v122, v142
	v_fma_f32 v187, v135, v123, v143
	v_fma_f32 v188, v136, v124, v144
	v_fma_f32 v189, v137, v125, v145
	v_fma_f32 v190, v134, v106, v142
	v_fma_f32 v191, v135, v107, v143
	v_fma_f32 v192, v136, v108, v144
	v_fma_f32 v193, v137, v109, v145
	v_fmac_f32_dpp v174, v110, v130 row_shr:1 row_mask:0xf bank_mask:0xf
	v_fmac_f32_dpp v175, v111, v131 row_shr:1 row_mask:0xf bank_mask:0xf
	v_fmac_f32_dpp v176, v112, v132 row_shr:1 row_mask:0xf bank_mask:0xf
	v_fmac_f32_dpp v177, v113, v133 row_shr:1 row_mask:0xf bank_mask:0xf
	v_fmac_f32_dpp v174, v110, v138 row_shl:1 row_mask:0xf bank_mask:0xf
	v_fmac_f32_dpp v175, v111, v139 row_shl:1 row_mask:0xf bank_mask:0xf
	v_fmac_f32_dpp v176, v112, v140 row_shl:1 row_mask:0xf bank_mask:0xf
	v_fmac_f32_dpp v177, v113, v141 row_shl:1 row_mask:0xf bank_mask:0xf
	v_fmac_f32_dpp v174, v126, v138 row_shr:15 row_mask:0xf bank_mask:0xf
	v_fmac_f32_dpp v175, v127, v139 row_shr:15 row_mask:0xf bank_mask:0xf
	v_fmac_f32_dpp v176, v128, v140 row_shr:15 row_mask:0xf bank_mask:0xf
	v_fmac_f32_dpp v177, v129, v141 row_shr:15 row_mask:0xf bank_mask:0xf
	v_fmac_f32_dpp v178, v126, v130 row_shr:1 row_mask:0xf bank_mask:0xf
	v_fmac_f32_dpp v179, v127, v131 row_shr:1 row_mask:0xf bank_mask:0xf
	v_fmac_f32_dpp v180, v128, v132 row_shr:1 row_mask:0xf bank_mask:0xf
	v_fmac_f32_dpp v181, v129, v133 row_shr:1 row_mask:0xf bank_mask:0xf
	v_fmac_f32_dpp v178, v110, v130 row_shl:15 row_mask:0xf bank_mask:0xf
	v_fmac_f32_dpp v179, v111, v131 row_shl:15 row_mask:0xf bank_mask:0xf
	v_fmac_f32_dpp v180, v112, v132 row_shl:15 row_mask:0xf bank_mask:0xf
	v_fmac_f32_dpp v181, v113, v133 row_shl:15 row_mask:0xf bank_mask:0xf
	v_fmac_f32_dpp v178, v126, v138 row_shl:1 row_mask:0xf bank_mask:0xf
	v_fmac_f32_dpp v179, v127, v139 row_shl:1 row_mask:0xf bank_mask:0xf
	v_fmac_f32_dpp v180, v128, v140 row_shl:1 row_mask:0xf bank_mask:0xf
	v_fmac_f32_dpp v181, v129, v141 row_shl:1 row_mask:0xf bank_mask:0xf
	v_fmac_f32_dpp v178, v122, v138 row_shr:15 row_mask:0xf bank_mask:0xf
	v_fmac_f32_dpp v179, v123, v139 row_shr:15 row_mask:0xf bank_mask:0xf
	v_fmac_f32_dpp v180, v124, v140 row_shr:15 row_mask:0xf bank_mask:0xf
	v_fmac_f32_dpp v181, v125, v141 row_shr:15 row_mask:0xf bank_mask:0xf
	v_fmac_f32_dpp v186, v122, v130 row_shr:1 row_mask:0xf bank_mask:0xf
	v_fmac_f32_dpp v187, v123, v131 row_shr:1 row_mask:0xf bank_mask:0xf
	v_fmac_f32_dpp v188, v124, v132 row_shr:1 row_mask:0xf bank_mask:0xf
	v_fmac_f32_dpp v189, v125, v133 row_shr:1 row_mask:0xf bank_mask:0xf
	v_fmac_f32_dpp v186, v126, v130 row_shl:15 row_mask:0xf bank_mask:0xf
	v_fmac_f32_dpp v187, v127, v131 row_shl:15 row_mask:0xf bank_mask:0xf
	v_fmac_f32_dpp v188, v128, v132 row_shl:15 row_mask:0xf bank_mask:0xf
	v_fmac_f32_dpp v189, v129, v133 row_shl:15 row_mask:0xf bank_mask:0xf
	v_fmac_f32_dpp v186, v122, v138 row_shl:1 row_mask:0xf bank_mask:0xf
	v_fmac_f32_dpp v187, v123, v139 row_shl:1 row_mask:0xf bank_mask:0xf
	v_fmac_f32_dpp v188, v124, v140 row_shl:1 row_mask:0xf bank_mask:0xf
	v_fmac_f32_dpp v189, v125, v141 row_shl:1 row_mask:0xf bank_mask:0xf
	v_fmac_f32_dpp v186, v106, v138 row_shr:15 row_mask:0xf bank_mask:0xf
; #define DPP_UP(v) __int_as_float(__builtin_amdgcn_update_dpp(0, __float_as_int(v), 0x121, 0xf, 0xf, false))
; #define DPP_DN(v) __int_as_float(__builtin_amdgcn_update_dpp(0, __float_as_int(v), 0x12F, 0xf, 0xf, false))
;     __device__ __forceinline__ void operator()(const f32x4 (&acc)[2][2][4][2], const Unit& u, int wr, int wc, int fr_in, int fq_in) const {
;     ...
;                     const f32x4 k0 = *(const f32x4*)(fk + co + ch), k1 = *(const f32x4*)(fk + DFF2 + co + ch), k2 = *(const f32x4*)(fk + 2 * DFF2 + co + ch), bb = *(const f32x4*)(fb + co + ch);
;                     f32x4 up_prev = (f32x4){0.f, 0.f, 0.f, 0.f}, up_cur, dn_cur, dn_next;
; #pragma unroll
;                     for (int j = 0; j < 4; ++j) dn_cur[j] = DPP_DN(acc[ai][pass][0][n][j]);
; #pragma unroll
;                     for (int m = 0; m < 4; ++m) {
;                         const f32x4 xv = acc[ai][pass][m][n];
; #pragma unroll
;                         for (int j = 0; j < 4; ++j) { up_cur[j] = DPP_UP(xv[j]); dn_next[j] = (m < 3) ? DPP_DN(acc[ai][pass][m < 3 ? m + 1 : 3][n][j]) : 0.f; }
;                         const f32x4 xp = f0 ? up_prev : up_cur, xn = f15 ? dn_next : dn_cur;
;                         const f32x4 c = (k0 * xp + k1 * xv) + (k2 * xn + bb);
;                         if (pass == 0) o[m] = c;
;                         else { f32x4 e;
; #pragma unroll
;                             for (int j = 0; j < 4; ++j) e[j] = __builtin_amdgcn_rcpf(1.0f + __builtin_amdgcn_exp2f(c[j] * -1.4426950408889634f));
;                             o[m] = o[m] * (c * e); }
;                         up_prev = up_cur; dn_cur = dn_next; }
	v_fmac_f32_dpp v187, v107, v139 row_shr:15 row_mask:0xf bank_mask:0xf
	v_fmac_f32_dpp v188, v108, v140 row_shr:15 row_mask:0xf bank_mask:0xf
	v_fmac_f32_dpp v189, v109, v141 row_shr:15 row_mask:0xf bank_mask:0xf
	v_fmac_f32_dpp v190, v106, v130 row_shr:1 row_mask:0xf bank_mask:0xf
	v_fmac_f32_dpp v191, v107, v131 row_shr:1 row_mask:0xf bank_mask:0xf
	v_fmac_f32_dpp v192, v108, v132 row_shr:1 row_mask:0xf bank_mask:0xf
	v_fmac_f32_dpp v193, v109, v133 row_shr:1 row_mask:0xf bank_mask:0xf
	v_fmac_f32_dpp v190, v122, v130 row_shl:15 row_mask:0xf bank_mask:0xf
	v_fmac_f32_dpp v191, v123, v131 row_shl:15 row_mask:0xf bank_mask:0xf
	v_fmac_f32_dpp v192, v124, v132 row_shl:15 row_mask:0xf bank_mask:0xf
	v_fmac_f32_dpp v193, v125, v133 row_shl:15 row_mask:0xf bank_mask:0xf
	v_fmac_f32_dpp v190, v106, v138 row_shl:1 row_mask:0xf bank_mask:0xf
	v_fmac_f32_dpp v191, v107, v139 row_shl:1 row_mask:0xf bank_mask:0xf
	v_fmac_f32_dpp v192, v108, v140 row_shl:1 row_mask:0xf bank_mask:0xf
	v_fmac_f32_dpp v193, v109, v141 row_shl:1 row_mask:0xf bank_mask:0xf
	v_fma_f32 v226, v162, v102, v170
	v_fma_f32 v227, v163, v103, v171
	v_fma_f32 v228, v164, v104, v172
	v_fma_f32 v229, v165, v105, v173
	v_fma_f32 v230, v162, v118, v170
	v_fma_f32 v231, v163, v119, v171
	v_fma_f32 v232, v164, v120, v172
	v_fma_f32 v233, v165, v121, v173
	v_fma_f32 v234, v162, v114, v170
	v_fma_f32 v235, v163, v115, v171
	v_fma_f32 v236, v164, v116, v172
	v_fma_f32 v237, v165, v117, v173
	v_fma_f32 v238, v162, v98, v170
	v_fma_f32 v239, v163, v99, v171
	v_fma_f32 v240, v164, v100, v172
	v_fma_f32 v241, v165, v101, v173
	v_fmac_f32_dpp v226, v102, v158 row_shr:1 row_mask:0xf bank_mask:0xf
	v_fmac_f32_dpp v227, v103, v159 row_shr:1 row_mask:0xf bank_mask:0xf
	v_fmac_f32_dpp v228, v104, v160 row_shr:1 row_mask:0xf bank_mask:0xf
	v_fmac_f32_dpp v229, v105, v161 row_shr:1 row_mask:0xf bank_mask:0xf
	v_fmac_f32_dpp v226, v102, v166 row_shl:1 row_mask:0xf bank_mask:0xf
	v_fmac_f32_dpp v227, v103, v167 row_shl:1 row_mask:0xf bank_mask:0xf
	v_fmac_f32_dpp v228, v104, v168 row_shl:1 row_mask:0xf bank_mask:0xf
	v_fmac_f32_dpp v229, v105, v169 row_shl:1 row_mask:0xf bank_mask:0xf
	v_fmac_f32_dpp v226, v118, v166 row_shr:15 row_mask:0xf bank_mask:0xf
	v_fmac_f32_dpp v227, v119, v167 row_shr:15 row_mask:0xf bank_mask:0xf
	v_fmac_f32_dpp v228, v120, v168 row_shr:15 row_mask:0xf bank_mask:0xf
	v_fmac_f32_dpp v229, v121, v169 row_shr:15 row_mask:0xf bank_mask:0xf
	v_fmac_f32_dpp v230, v118, v158 row_shr:1 row_mask:0xf bank_mask:0xf
	v_fmac_f32_dpp v231, v119, v159 row_shr:1 row_mask:0xf bank_mask:0xf
	v_fmac_f32_dpp v232, v120, v160 row_shr:1 row_mask:0xf bank_mask:0xf
	v_fmac_f32_dpp v233, v121, v161 row_shr:1 row_mask:0xf bank_mask:0xf
	v_fmac_f32_dpp v230, v102, v158 row_shl:15 row_mask:0xf bank_mask:0xf
	v_fmac_f32_dpp v231, v103, v159 row_shl:15 row_mask:0xf bank_mask:0xf
	v_fmac_f32_dpp v232, v104, v160 row_shl:15 row_mask:0xf bank_mask:0xf
	v_fmac_f32_dpp v233, v105, v161 row_shl:15 row_mask:0xf bank_mask:0xf
	v_fmac_f32_dpp v230, v118, v166 row_shl:1 row_mask:0xf bank_mask:0xf
	v_fmac_f32_dpp v231, v119, v167 row_shl:1 row_mask:0xf bank_mask:0xf
	v_fmac_f32_dpp v232, v120, v168 row_shl:1 row_mask:0xf bank_mask:0xf
	v_fmac_f32_dpp v233, v121, v169 row_shl:1 row_mask:0xf bank_mask:0xf
	v_fmac_f32_dpp v230, v114, v166 row_shr:15 row_mask:0xf bank_mask:0xf
	v_fmac_f32_dpp v231, v115, v167 row_shr:15 row_mask:0xf bank_mask:0xf
	v_fmac_f32_dpp v232, v116, v168 row_shr:15 row_mask:0xf bank_mask:0xf
	v_fmac_f32_dpp v233, v117, v169 row_shr:15 row_mask:0xf bank_mask:0xf
	v_fmac_f32_dpp v234, v114, v158 row_shr:1 row_mask:0xf bank_mask:0xf
	v_fmac_f32_dpp v235, v115, v159 row_shr:1 row_mask:0xf bank_mask:0xf
	v_fmac_f32_dpp v236, v116, v160 row_shr:1 row_mask:0xf bank_mask:0xf
	v_fmac_f32_dpp v237, v117, v161 row_shr:1 row_mask:0xf bank_mask:0xf
	v_fmac_f32_dpp v234, v118, v158 row_shl:15 row_mask:0xf bank_mask:0xf
	v_fmac_f32_dpp v235, v119, v159 row_shl:15 row_mask:0xf bank_mask:0xf
	v_fmac_f32_dpp v236, v120, v160 row_shl:15 row_mask:0xf bank_mask:0xf
	v_fmac_f32_dpp v237, v121, v161 row_shl:15 row_mask:0xf bank_mask:0xf
	v_fmac_f32_dpp v234, v114, v166 row_shl:1 row_mask:0xf bank_mask:0xf
	v_fmac_f32_dpp v235, v115, v167 row_shl:1 row_mask:0xf bank_mask:0xf
	v_fmac_f32_dpp v236, v116, v168 row_shl:1 row_mask:0xf bank_mask:0xf
	v_fmac_f32_dpp v237, v117, v169 row_shl:1 row_mask:0xf bank_mask:0xf
	v_fmac_f32_dpp v234, v98, v166 row_shr:15 row_mask:0xf bank_mask:0xf
	v_fmac_f32_dpp v235, v99, v167 row_shr:15 row_mask:0xf bank_mask:0xf
	v_fmac_f32_dpp v236, v100, v168 row_shr:15 row_mask:0xf bank_mask:0xf
	v_fmac_f32_dpp v237, v101, v169 row_shr:15 row_mask:0xf bank_mask:0xf
	v_fmac_f32_dpp v238, v98, v158 row_shr:1 row_mask:0xf bank_mask:0xf
	v_fmac_f32_dpp v239, v99, v159 row_shr:1 row_mask:0xf bank_mask:0xf
	v_fmac_f32_dpp v240, v100, v160 row_shr:1 row_mask:0xf bank_mask:0xf
	v_fmac_f32_dpp v241, v101, v161 row_shr:1 row_mask:0xf bank_mask:0xf
	v_fmac_f32_dpp v238, v114, v158 row_shl:15 row_mask:0xf bank_mask:0xf
	v_fmac_f32_dpp v239, v115, v159 row_shl:15 row_mask:0xf bank_mask:0xf
	v_fmac_f32_dpp v240, v116, v160 row_shl:15 row_mask:0xf bank_mask:0xf
	v_fmac_f32_dpp v241, v117, v161 row_shl:15 row_mask:0xf bank_mask:0xf
	v_fmac_f32_dpp v238, v98, v166 row_shl:1 row_mask:0xf bank_mask:0xf
	v_fmac_f32_dpp v239, v99, v167 row_shl:1 row_mask:0xf bank_mask:0xf
	v_fmac_f32_dpp v240, v100, v168 row_shl:1 row_mask:0xf bank_mask:0xf
	v_fmac_f32_dpp v241, v101, v169 row_shl:1 row_mask:0xf bank_mask:0xf
	v_mul_f32_e32 v242, 0xbfb8aa3b, v226
	v_mul_f32_e32 v243, 0xbfb8aa3b, v227
	v_mul_f32_e32 v244, 0xbfb8aa3b, v228
; #define DPP_UP(v) __int_as_float(__builtin_amdgcn_update_dpp(0, __float_as_int(v), 0x121, 0xf, 0xf, false))
;     __device__ __forceinline__ void operator()(const f32x4 (&acc)[2][2][4][2], const Unit& u, int wr, int wc, int fr_in, int fq_in) const {
;     ...
;                     const f32x4 k0 = *(const f32x4*)(fk + co + ch), k1 = *(const f32x4*)(fk + DFF2 + co + ch), k2 = *(const f32x4*)(fk + 2 * DFF2 + co + ch), bb = *(const f32x4*)(fb + co + ch);
;                     f32x4 up_prev = (f32x4){0.f, 0.f, 0.f, 0.f}, up_cur, dn_cur, dn_next;
; #pragma unroll
;                     for (int j = 0; j < 4; ++j) dn_cur[j] = DPP_DN(acc[ai][pass][0][n][j]);
; #pragma unroll
;                     for (int m = 0; m < 4; ++m) {
;                         const f32x4 xv = acc[ai][pass][m][n];
; #pragma unroll
;                         for (int j = 0; j < 4; ++j) { up_cur[j] = DPP_UP(xv[j]); dn_next[j] = (m < 3) ? DPP_DN(acc[ai][pass][m < 3 ? m + 1 : 3][n][j]) : 0.f; }
;                         const f32x4 xp = f0 ? up_prev : up_cur, xn = f15 ? dn_next : dn_cur;
;                         const f32x4 c = (k0 * xp + k1 * xv) + (k2 * xn + bb);
;                         if (pass == 0) o[m] = c;
;                         else { f32x4 e;
; #pragma unroll
;                             for (int j = 0; j < 4; ++j) e[j] = __builtin_amdgcn_rcpf(1.0f + __builtin_amdgcn_exp2f(c[j] * -1.4426950408889634f));
;                             o[m] = o[m] * (c * e); }
;                         up_prev = up_cur; dn_cur = dn_next; }
;                 }
;                 if (n == 0) {
; #pragma unroll
;                     for (int m = 0; m < 4; ++m) { wlo[m].x = cvt_pk_bf16(o[m][0], o[m][1]); wlo[m].y = cvt_pk_bf16(o[m][2], o[m][3]); }
;                 } else {
; #pragma unroll
;                     for (int m = 0; m < 4; ++m) { u32x4 w; w.x = wlo[m].x; w.y = wlo[m].y; w.z = cvt_pk_bf16(o[m][0], o[m][1]); w.w = cvt_pk_bf16(o[m][2], o[m][3]);
;                         *(u32x4*)(base + off0 + (unsigned)(ai * HALF + m * 16) * (DFF * 2u)) = w; }
;                 }
;                 if (fr < 2 || fr >= 14) { const int k = fr < 2 ? fr : fr - 12;
;                     const f32x4 xv = fr < 2 ? acc[ai][0][0][n] : acc[ai][0][3][n], yv = fr < 2 ? acc[ai][1][0][n] : acc[ai][1][3][n];
;                     char* sp = sbase + (size_t)((2 * ai + wr) * 4 + k) * (DFF2 * 2) + (size_t)ch * 2;
	v_mul_f32_e32 v245, 0xbfb8aa3b, v229
	v_mul_f32_e32 v246, 0xbfb8aa3b, v230
	v_mul_f32_e32 v247, 0xbfb8aa3b, v231
	v_mul_f32_e32 v248, 0xbfb8aa3b, v232
	v_mul_f32_e32 v249, 0xbfb8aa3b, v233
	v_exp_f32_e32 v242, v242
	v_exp_f32_e32 v243, v243
	v_exp_f32_e32 v244, v244
	v_exp_f32_e32 v245, v245
	v_exp_f32_e32 v246, v246
	v_exp_f32_e32 v247, v247
	v_exp_f32_e32 v248, v248
	v_exp_f32_e32 v249, v249
	v_add_f32_e32 v242, 1.0, v242
	v_add_f32_e32 v243, 1.0, v243
	v_add_f32_e32 v244, 1.0, v244
	v_add_f32_e32 v245, 1.0, v245
	v_add_f32_e32 v246, 1.0, v246
	v_add_f32_e32 v247, 1.0, v247
	v_add_f32_e32 v248, 1.0, v248
	v_add_f32_e32 v249, 1.0, v249
	v_rcp_f32_e32 v242, v242
	v_rcp_f32_e32 v243, v243
	v_rcp_f32_e32 v244, v244
	v_rcp_f32_e32 v245, v245
	v_rcp_f32_e32 v246, v246
	v_rcp_f32_e32 v247, v247
	v_rcp_f32_e32 v248, v248
	v_rcp_f32_e32 v249, v249
	v_mul_f32_e32 v242, v226, v242
	v_mul_f32_e32 v243, v227, v243
	v_mul_f32_e32 v244, v228, v244
	v_mul_f32_e32 v245, v229, v245
	v_mul_f32_e32 v246, v230, v246
	v_mul_f32_e32 v247, v231, v247
	v_mul_f32_e32 v248, v232, v248
	v_mul_f32_e32 v249, v233, v249
	v_mul_f32_e32 v174, v174, v242
	v_mul_f32_e32 v175, v175, v243
	v_mul_f32_e32 v176, v176, v244
	v_mul_f32_e32 v177, v177, v245
	v_mul_f32_e32 v178, v178, v246
	v_mul_f32_e32 v179, v179, v247
	v_mul_f32_e32 v180, v180, v248
	v_mul_f32_e32 v181, v181, v249
	v_mul_f32_e32 v242, 0xbfb8aa3b, v234
	v_mul_f32_e32 v243, 0xbfb8aa3b, v235
	v_mul_f32_e32 v244, 0xbfb8aa3b, v236
	v_mul_f32_e32 v245, 0xbfb8aa3b, v237
	v_mul_f32_e32 v246, 0xbfb8aa3b, v238
	v_mul_f32_e32 v247, 0xbfb8aa3b, v239
	v_mul_f32_e32 v248, 0xbfb8aa3b, v240
	v_mul_f32_e32 v249, 0xbfb8aa3b, v241
	v_exp_f32_e32 v242, v242
	v_exp_f32_e32 v243, v243
	v_exp_f32_e32 v244, v244
	v_exp_f32_e32 v245, v245
	v_exp_f32_e32 v246, v246
	v_exp_f32_e32 v247, v247
	v_exp_f32_e32 v248, v248
	v_exp_f32_e32 v249, v249
	v_add_f32_e32 v242, 1.0, v242
	v_add_f32_e32 v243, 1.0, v243
	v_add_f32_e32 v244, 1.0, v244
	v_add_f32_e32 v245, 1.0, v245
	v_add_f32_e32 v246, 1.0, v246
	v_add_f32_e32 v247, 1.0, v247
	v_add_f32_e32 v248, 1.0, v248
	v_add_f32_e32 v249, 1.0, v249
	v_rcp_f32_e32 v242, v242
	v_rcp_f32_e32 v243, v243
	v_rcp_f32_e32 v244, v244
	v_rcp_f32_e32 v245, v245
	v_rcp_f32_e32 v246, v246
	v_rcp_f32_e32 v247, v247
	v_rcp_f32_e32 v248, v248
	v_rcp_f32_e32 v249, v249
	v_mul_f32_e32 v242, v234, v242
	v_mul_f32_e32 v243, v235, v243
	v_mul_f32_e32 v244, v236, v244
	v_mul_f32_e32 v245, v237, v245
	v_mul_f32_e32 v246, v238, v246
	v_mul_f32_e32 v247, v239, v247
	v_mul_f32_e32 v248, v240, v248
	v_mul_f32_e32 v249, v241, v249
	v_mul_f32_e32 v186, v186, v242
	v_mul_f32_e32 v187, v187, v243
	v_mul_f32_e32 v188, v188, v244
	v_mul_f32_e32 v189, v189, v245
	v_mul_f32_e32 v190, v190, v246
	v_mul_f32_e32 v191, v191, v247
	v_mul_f32_e32 v192, v192, v248
	v_mul_f32_e32 v193, v193, v249
	v_cvt_pk_bf16_f32 v110, v174, v175
	v_cvt_pk_bf16_f32 v111, v176, v177
	v_cvt_pk_bf16_f32 v126, v178, v179
	v_cvt_pk_bf16_f32 v127, v180, v181
	v_cvt_pk_bf16_f32 v122, v186, v187
	v_cvt_pk_bf16_f32 v123, v188, v189
	v_cvt_pk_bf16_f32 v106, v190, v191
	v_cvt_pk_bf16_f32 v107, v192, v193
	v_cndmask_b32_e64 v202, v40, v44, s[12:13]
	v_cndmask_b32_e64 v203, v41, v45, s[12:13]
	v_cndmask_b32_e64 v204, v42, v46, s[12:13]
	v_cndmask_b32_e64 v205, v43, v47, s[12:13]
	v_cndmask_b32_e64 v206, v32, v36, s[12:13]
	v_cndmask_b32_e64 v207, v33, v37, s[12:13]
	v_cndmask_b32_e64 v208, v34, v38, s[12:13]
	v_cndmask_b32_e64 v209, v35, v39, s[12:13]
	v_cvt_pk_bf16_f32 v250, v202, v203
	v_cvt_pk_bf16_f32 v251, v204, v205
	v_cvt_pk_bf16_f32 v252, v206, v207
	v_cvt_pk_bf16_f32 v253, v208, v209
	s_add_u32 s10, s10, 0x16000
	s_addc_u32 s11, s11, 0
	s_mov_b64 s[42:43], exec
	s_and_b64 exec, exec, s[22:23]
	global_store_dwordx2 v195, v[250:251], s[10:11]
	global_store_dwordx2 v197, v[252:253], s[10:11]
	s_mov_b64 exec, s[42:43]
	v_fma_f32 v174, v134, v44, v142
	v_fma_f32 v175, v135, v45, v143
	v_fma_f32 v176, v136, v46, v144
	v_fma_f32 v177, v137, v47, v145
	v_fma_f32 v178, v134, v60, v142
	v_fma_f32 v179, v135, v61, v143
	v_fma_f32 v180, v136, v62, v144
	v_fma_f32 v181, v137, v63, v145
	v_fma_f32 v186, v134, v56, v142
	v_fma_f32 v187, v135, v57, v143
	v_fma_f32 v188, v136, v58, v144
	v_fma_f32 v189, v137, v59, v145
	v_fma_f32 v190, v134, v40, v142
	v_fma_f32 v191, v135, v41, v143
	v_fma_f32 v192, v136, v42, v144
	v_fma_f32 v193, v137, v43, v145
	v_fmac_f32_dpp v174, v44, v130 row_shr:1 row_mask:0xf bank_mask:0xf
	v_fmac_f32_dpp v175, v45, v131 row_shr:1 row_mask:0xf bank_mask:0xf
	v_fmac_f32_dpp v176, v46, v132 row_shr:1 row_mask:0xf bank_mask:0xf
	v_fmac_f32_dpp v177, v47, v133 row_shr:1 row_mask:0xf bank_mask:0xf
	v_fmac_f32_dpp v174, v44, v138 row_shl:1 row_mask:0xf bank_mask:0xf
	v_fmac_f32_dpp v175, v45, v139 row_shl:1 row_mask:0xf bank_mask:0xf
	v_fmac_f32_dpp v176, v46, v140 row_shl:1 row_mask:0xf bank_mask:0xf
	v_fmac_f32_dpp v177, v47, v141 row_shl:1 row_mask:0xf bank_mask:0xf
	v_fmac_f32_dpp v174, v60, v138 row_shr:15 row_mask:0xf bank_mask:0xf
	v_fmac_f32_dpp v175, v61, v139 row_shr:15 row_mask:0xf bank_mask:0xf
	v_fmac_f32_dpp v176, v62, v140 row_shr:15 row_mask:0xf bank_mask:0xf
	v_fmac_f32_dpp v177, v63, v141 row_shr:15 row_mask:0xf bank_mask:0xf
	v_fmac_f32_dpp v178, v60, v130 row_shr:1 row_mask:0xf bank_mask:0xf
	v_fmac_f32_dpp v179, v61, v131 row_shr:1 row_mask:0xf bank_mask:0xf
	v_fmac_f32_dpp v180, v62, v132 row_shr:1 row_mask:0xf bank_mask:0xf
	v_fmac_f32_dpp v181, v63, v133 row_shr:1 row_mask:0xf bank_mask:0xf
	v_fmac_f32_dpp v178, v44, v130 row_shl:15 row_mask:0xf bank_mask:0xf
	v_fmac_f32_dpp v179, v45, v131 row_shl:15 row_mask:0xf bank_mask:0xf
; #define DPP_UP(v) __int_as_float(__builtin_amdgcn_update_dpp(0, __float_as_int(v), 0x121, 0xf, 0xf, false))
; #define DPP_DN(v) __int_as_float(__builtin_amdgcn_update_dpp(0, __float_as_int(v), 0x12F, 0xf, 0xf, false))
;     __device__ __forceinline__ void operator()(const f32x4 (&acc)[2][2][4][2], const Unit& u, int wr, int wc, int fr_in, int fq_in) const {
;     ...
;                     const f32x4 k0 = *(const f32x4*)(fk + co + ch), k1 = *(const f32x4*)(fk + DFF2 + co + ch), k2 = *(const f32x4*)(fk + 2 * DFF2 + co + ch), bb = *(const f32x4*)(fb + co + ch);
;                     f32x4 up_prev = (f32x4){0.f, 0.f, 0.f, 0.f}, up_cur, dn_cur, dn_next;
; #pragma unroll
;                     for (int j = 0; j < 4; ++j) dn_cur[j] = DPP_DN(acc[ai][pass][0][n][j]);
; #pragma unroll
;                     for (int m = 0; m < 4; ++m) {
;                         const f32x4 xv = acc[ai][pass][m][n];
; #pragma unroll
;                         for (int j = 0; j < 4; ++j) { up_cur[j] = DPP_UP(xv[j]); dn_next[j] = (m < 3) ? DPP_DN(acc[ai][pass][m < 3 ? m + 1 : 3][n][j]) : 0.f; }
;                         const f32x4 xp = f0 ? up_prev : up_cur, xn = f15 ? dn_next : dn_cur;
;                         const f32x4 c = (k0 * xp + k1 * xv) + (k2 * xn + bb);
;                         if (pass == 0) o[m] = c;
;                         else { f32x4 e;
; #pragma unroll
;                             for (int j = 0; j < 4; ++j) e[j] = __builtin_amdgcn_rcpf(1.0f + __builtin_amdgcn_exp2f(c[j] * -1.4426950408889634f));
;                             o[m] = o[m] * (c * e); }
;                         up_prev = up_cur; dn_cur = dn_next; }
	v_fmac_f32_dpp v180, v46, v132 row_shl:15 row_mask:0xf bank_mask:0xf
	v_fmac_f32_dpp v181, v47, v133 row_shl:15 row_mask:0xf bank_mask:0xf
	v_fmac_f32_dpp v178, v60, v138 row_shl:1 row_mask:0xf bank_mask:0xf
	v_fmac_f32_dpp v179, v61, v139 row_shl:1 row_mask:0xf bank_mask:0xf
	v_fmac_f32_dpp v180, v62, v140 row_shl:1 row_mask:0xf bank_mask:0xf
	v_fmac_f32_dpp v181, v63, v141 row_shl:1 row_mask:0xf bank_mask:0xf
	v_fmac_f32_dpp v178, v56, v138 row_shr:15 row_mask:0xf bank_mask:0xf
	v_fmac_f32_dpp v179, v57, v139 row_shr:15 row_mask:0xf bank_mask:0xf
	v_fmac_f32_dpp v180, v58, v140 row_shr:15 row_mask:0xf bank_mask:0xf
	v_fmac_f32_dpp v181, v59, v141 row_shr:15 row_mask:0xf bank_mask:0xf
	v_fmac_f32_dpp v186, v56, v130 row_shr:1 row_mask:0xf bank_mask:0xf
	v_fmac_f32_dpp v187, v57, v131 row_shr:1 row_mask:0xf bank_mask:0xf
	v_fmac_f32_dpp v188, v58, v132 row_shr:1 row_mask:0xf bank_mask:0xf
	v_fmac_f32_dpp v189, v59, v133 row_shr:1 row_mask:0xf bank_mask:0xf
	v_fmac_f32_dpp v186, v60, v130 row_shl:15 row_mask:0xf bank_mask:0xf
	v_fmac_f32_dpp v187, v61, v131 row_shl:15 row_mask:0xf bank_mask:0xf
	v_fmac_f32_dpp v188, v62, v132 row_shl:15 row_mask:0xf bank_mask:0xf
	v_fmac_f32_dpp v189, v63, v133 row_shl:15 row_mask:0xf bank_mask:0xf
	v_fmac_f32_dpp v186, v56, v138 row_shl:1 row_mask:0xf bank_mask:0xf
	v_fmac_f32_dpp v187, v57, v139 row_shl:1 row_mask:0xf bank_mask:0xf
	v_fmac_f32_dpp v188, v58, v140 row_shl:1 row_mask:0xf bank_mask:0xf
	v_fmac_f32_dpp v189, v59, v141 row_shl:1 row_mask:0xf bank_mask:0xf
	v_fmac_f32_dpp v186, v40, v138 row_shr:15 row_mask:0xf bank_mask:0xf
	v_fmac_f32_dpp v187, v41, v139 row_shr:15 row_mask:0xf bank_mask:0xf
	v_fmac_f32_dpp v188, v42, v140 row_shr:15 row_mask:0xf bank_mask:0xf
	v_fmac_f32_dpp v189, v43, v141 row_shr:15 row_mask:0xf bank_mask:0xf
	v_fmac_f32_dpp v190, v40, v130 row_shr:1 row_mask:0xf bank_mask:0xf
	v_fmac_f32_dpp v191, v41, v131 row_shr:1 row_mask:0xf bank_mask:0xf
	v_fmac_f32_dpp v192, v42, v132 row_shr:1 row_mask:0xf bank_mask:0xf
	v_fmac_f32_dpp v193, v43, v133 row_shr:1 row_mask:0xf bank_mask:0xf
	v_fmac_f32_dpp v190, v56, v130 row_shl:15 row_mask:0xf bank_mask:0xf
	v_fmac_f32_dpp v191, v57, v131 row_shl:15 row_mask:0xf bank_mask:0xf
	v_fmac_f32_dpp v192, v58, v132 row_shl:15 row_mask:0xf bank_mask:0xf
	v_fmac_f32_dpp v193, v59, v133 row_shl:15 row_mask:0xf bank_mask:0xf
	v_fmac_f32_dpp v190, v40, v138 row_shl:1 row_mask:0xf bank_mask:0xf
	v_fmac_f32_dpp v191, v41, v139 row_shl:1 row_mask:0xf bank_mask:0xf
	v_fmac_f32_dpp v192, v42, v140 row_shl:1 row_mask:0xf bank_mask:0xf
	v_fmac_f32_dpp v193, v43, v141 row_shl:1 row_mask:0xf bank_mask:0xf
	v_fma_f32 v226, v162, v36, v170
	v_fma_f32 v227, v163, v37, v171
	v_fma_f32 v228, v164, v38, v172
	v_fma_f32 v229, v165, v39, v173
	v_fma_f32 v230, v162, v52, v170
	v_fma_f32 v231, v163, v53, v171
	v_fma_f32 v232, v164, v54, v172
	v_fma_f32 v233, v165, v55, v173
	v_fma_f32 v234, v162, v48, v170
	v_fma_f32 v235, v163, v49, v171
	v_fma_f32 v236, v164, v50, v172
	v_fma_f32 v237, v165, v51, v173
	v_fma_f32 v238, v162, v32, v170
	v_fma_f32 v239, v163, v33, v171
	v_fma_f32 v240, v164, v34, v172
	v_fma_f32 v241, v165, v35, v173
	v_fmac_f32_dpp v226, v36, v158 row_shr:1 row_mask:0xf bank_mask:0xf
	v_fmac_f32_dpp v227, v37, v159 row_shr:1 row_mask:0xf bank_mask:0xf
	v_fmac_f32_dpp v228, v38, v160 row_shr:1 row_mask:0xf bank_mask:0xf
	v_fmac_f32_dpp v229, v39, v161 row_shr:1 row_mask:0xf bank_mask:0xf
	v_fmac_f32_dpp v226, v36, v166 row_shl:1 row_mask:0xf bank_mask:0xf
	v_fmac_f32_dpp v227, v37, v167 row_shl:1 row_mask:0xf bank_mask:0xf
	v_fmac_f32_dpp v228, v38, v168 row_shl:1 row_mask:0xf bank_mask:0xf
	v_fmac_f32_dpp v229, v39, v169 row_shl:1 row_mask:0xf bank_mask:0xf
	v_fmac_f32_dpp v226, v52, v166 row_shr:15 row_mask:0xf bank_mask:0xf
	v_fmac_f32_dpp v227, v53, v167 row_shr:15 row_mask:0xf bank_mask:0xf
	v_fmac_f32_dpp v228, v54, v168 row_shr:15 row_mask:0xf bank_mask:0xf
	v_fmac_f32_dpp v229, v55, v169 row_shr:15 row_mask:0xf bank_mask:0xf
	v_fmac_f32_dpp v230, v52, v158 row_shr:1 row_mask:0xf bank_mask:0xf
	v_fmac_f32_dpp v231, v53, v159 row_shr:1 row_mask:0xf bank_mask:0xf
	v_fmac_f32_dpp v232, v54, v160 row_shr:1 row_mask:0xf bank_mask:0xf
	v_fmac_f32_dpp v233, v55, v161 row_shr:1 row_mask:0xf bank_mask:0xf
	v_fmac_f32_dpp v230, v36, v158 row_shl:15 row_mask:0xf bank_mask:0xf
	v_fmac_f32_dpp v231, v37, v159 row_shl:15 row_mask:0xf bank_mask:0xf
	v_fmac_f32_dpp v232, v38, v160 row_shl:15 row_mask:0xf bank_mask:0xf
	v_fmac_f32_dpp v233, v39, v161 row_shl:15 row_mask:0xf bank_mask:0xf
	v_fmac_f32_dpp v230, v52, v166 row_shl:1 row_mask:0xf bank_mask:0xf
	v_fmac_f32_dpp v231, v53, v167 row_shl:1 row_mask:0xf bank_mask:0xf
	v_fmac_f32_dpp v232, v54, v168 row_shl:1 row_mask:0xf bank_mask:0xf
	v_fmac_f32_dpp v233, v55, v169 row_shl:1 row_mask:0xf bank_mask:0xf
	v_fmac_f32_dpp v230, v48, v166 row_shr:15 row_mask:0xf bank_mask:0xf
	v_fmac_f32_dpp v231, v49, v167 row_shr:15 row_mask:0xf bank_mask:0xf
	v_fmac_f32_dpp v232, v50, v168 row_shr:15 row_mask:0xf bank_mask:0xf
	v_fmac_f32_dpp v233, v51, v169 row_shr:15 row_mask:0xf bank_mask:0xf
	v_fmac_f32_dpp v234, v48, v158 row_shr:1 row_mask:0xf bank_mask:0xf
	v_fmac_f32_dpp v235, v49, v159 row_shr:1 row_mask:0xf bank_mask:0xf
	v_fmac_f32_dpp v236, v50, v160 row_shr:1 row_mask:0xf bank_mask:0xf
	v_fmac_f32_dpp v237, v51, v161 row_shr:1 row_mask:0xf bank_mask:0xf
	v_fmac_f32_dpp v234, v52, v158 row_shl:15 row_mask:0xf bank_mask:0xf
	v_fmac_f32_dpp v235, v53, v159 row_shl:15 row_mask:0xf bank_mask:0xf
	v_fmac_f32_dpp v236, v54, v160 row_shl:15 row_mask:0xf bank_mask:0xf
	v_fmac_f32_dpp v237, v55, v161 row_shl:15 row_mask:0xf bank_mask:0xf
; __device__ __forceinline__ unsigned cvt_pk_bf16(float lo, float hi) { unsigned r; asm volatile("v_cvt_pk_bf16_f32 %0, %1, %2" : "=v"(r) : "v"(lo), "v"(hi)); return r; }
;     __device__ __forceinline__ void operator()(const f32x4 (&acc)[2][2][4][2], const Unit& u, int wr, int wc, int fr_in, int fq_in) const {
;     ...
;                         else { f32x4 e;
; #pragma unroll
;                             for (int j = 0; j < 4; ++j) e[j] = __builtin_amdgcn_rcpf(1.0f + __builtin_amdgcn_exp2f(c[j] * -1.4426950408889634f));
;                             o[m] = o[m] * (c * e); }
;                         up_prev = up_cur; dn_cur = dn_next; }
;                 }
;                 if (n == 0) {
; #pragma unroll
;                     for (int m = 0; m < 4; ++m) { wlo[m].x = cvt_pk_bf16(o[m][0], o[m][1]); wlo[m].y = cvt_pk_bf16(o[m][2], o[m][3]); }
;                 } else {
; #pragma unroll
;                     for (int m = 0; m < 4; ++m) { u32x4 w; w.x = wlo[m].x; w.y = wlo[m].y; w.z = cvt_pk_bf16(o[m][0], o[m][1]); w.w = cvt_pk_bf16(o[m][2], o[m][3]);
;                         *(u32x4*)(base + off0 + (unsigned)(ai * HALF + m * 16) * (DFF * 2u)) = w; }
;                 }
;                 if (fr < 2 || fr >= 14) { const int k = fr < 2 ? fr : fr - 12;
;                     const f32x4 xv = fr < 2 ? acc[ai][0][0][n] : acc[ai][0][3][n], yv = fr < 2 ? acc[ai][1][0][n] : acc[ai][1][3][n];
;                     char* sp = sbase + (size_t)((2 * ai + wr) * 4 + k) * (DFF2 * 2) + (size_t)ch * 2;
;                     u32x2 a, b; a.x = cvt_pk_bf16(xv[0], xv[1]); a.y = cvt_pk_bf16(xv[2], xv[3]); b.x = cvt_pk_bf16(yv[0], yv[1]); b.y = cvt_pk_bf16(yv[2], yv[3]);
;                     *(u32x2*)sp = a; *(u32x2*)(sp + DFF * 2) = b; }
	v_fmac_f32_dpp v234, v48, v166 row_shl:1 row_mask:0xf bank_mask:0xf
	v_fmac_f32_dpp v235, v49, v167 row_shl:1 row_mask:0xf bank_mask:0xf
	v_fmac_f32_dpp v236, v50, v168 row_shl:1 row_mask:0xf bank_mask:0xf
	v_fmac_f32_dpp v237, v51, v169 row_shl:1 row_mask:0xf bank_mask:0xf
	v_fmac_f32_dpp v234, v32, v166 row_shr:15 row_mask:0xf bank_mask:0xf
	v_fmac_f32_dpp v235, v33, v167 row_shr:15 row_mask:0xf bank_mask:0xf
	v_fmac_f32_dpp v236, v34, v168 row_shr:15 row_mask:0xf bank_mask:0xf
	v_fmac_f32_dpp v237, v35, v169 row_shr:15 row_mask:0xf bank_mask:0xf
	v_fmac_f32_dpp v238, v32, v158 row_shr:1 row_mask:0xf bank_mask:0xf
	v_fmac_f32_dpp v239, v33, v159 row_shr:1 row_mask:0xf bank_mask:0xf
	v_fmac_f32_dpp v240, v34, v160 row_shr:1 row_mask:0xf bank_mask:0xf
	v_fmac_f32_dpp v241, v35, v161 row_shr:1 row_mask:0xf bank_mask:0xf
	v_fmac_f32_dpp v238, v48, v158 row_shl:15 row_mask:0xf bank_mask:0xf
	v_fmac_f32_dpp v239, v49, v159 row_shl:15 row_mask:0xf bank_mask:0xf
	v_fmac_f32_dpp v240, v50, v160 row_shl:15 row_mask:0xf bank_mask:0xf
	v_fmac_f32_dpp v241, v51, v161 row_shl:15 row_mask:0xf bank_mask:0xf
	v_fmac_f32_dpp v238, v32, v166 row_shl:1 row_mask:0xf bank_mask:0xf
	v_fmac_f32_dpp v239, v33, v167 row_shl:1 row_mask:0xf bank_mask:0xf
	v_fmac_f32_dpp v240, v34, v168 row_shl:1 row_mask:0xf bank_mask:0xf
	v_fmac_f32_dpp v241, v35, v169 row_shl:1 row_mask:0xf bank_mask:0xf
	v_mul_f32_e32 v242, 0xbfb8aa3b, v226
	v_mul_f32_e32 v243, 0xbfb8aa3b, v227
	v_mul_f32_e32 v244, 0xbfb8aa3b, v228
	v_mul_f32_e32 v245, 0xbfb8aa3b, v229
	v_mul_f32_e32 v246, 0xbfb8aa3b, v230
	v_mul_f32_e32 v247, 0xbfb8aa3b, v231
	v_mul_f32_e32 v248, 0xbfb8aa3b, v232
	v_mul_f32_e32 v249, 0xbfb8aa3b, v233
	v_exp_f32_e32 v242, v242
	v_exp_f32_e32 v243, v243
	v_exp_f32_e32 v244, v244
	v_exp_f32_e32 v245, v245
	v_exp_f32_e32 v246, v246
	v_exp_f32_e32 v247, v247
	v_exp_f32_e32 v248, v248
	v_exp_f32_e32 v249, v249
	v_add_f32_e32 v242, 1.0, v242
	v_add_f32_e32 v243, 1.0, v243
	v_add_f32_e32 v244, 1.0, v244
	v_add_f32_e32 v245, 1.0, v245
	v_add_f32_e32 v246, 1.0, v246
	v_add_f32_e32 v247, 1.0, v247
	v_add_f32_e32 v248, 1.0, v248
	v_add_f32_e32 v249, 1.0, v249
	v_rcp_f32_e32 v242, v242
	v_rcp_f32_e32 v243, v243
	v_rcp_f32_e32 v244, v244
	v_rcp_f32_e32 v245, v245
	v_rcp_f32_e32 v246, v246
	v_rcp_f32_e32 v247, v247
	v_rcp_f32_e32 v248, v248
	v_rcp_f32_e32 v249, v249
	v_mul_f32_e32 v242, v226, v242
	v_mul_f32_e32 v243, v227, v243
	v_mul_f32_e32 v244, v228, v244
	v_mul_f32_e32 v245, v229, v245
	v_mul_f32_e32 v246, v230, v246
	v_mul_f32_e32 v247, v231, v247
	v_mul_f32_e32 v248, v232, v248
	v_mul_f32_e32 v249, v233, v249
	v_mul_f32_e32 v174, v174, v242
	v_mul_f32_e32 v175, v175, v243
	v_mul_f32_e32 v176, v176, v244
	v_mul_f32_e32 v177, v177, v245
	v_mul_f32_e32 v178, v178, v246
	v_mul_f32_e32 v179, v179, v247
	v_mul_f32_e32 v180, v180, v248
	v_mul_f32_e32 v181, v181, v249
	v_mul_f32_e32 v242, 0xbfb8aa3b, v234
	v_mul_f32_e32 v243, 0xbfb8aa3b, v235
	v_mul_f32_e32 v244, 0xbfb8aa3b, v236
	v_mul_f32_e32 v245, 0xbfb8aa3b, v237
	v_mul_f32_e32 v246, 0xbfb8aa3b, v238
	v_mul_f32_e32 v247, 0xbfb8aa3b, v239
	v_mul_f32_e32 v248, 0xbfb8aa3b, v240
	v_mul_f32_e32 v249, 0xbfb8aa3b, v241
	v_exp_f32_e32 v242, v242
	v_exp_f32_e32 v243, v243
	v_exp_f32_e32 v244, v244
	v_exp_f32_e32 v245, v245
	v_exp_f32_e32 v246, v246
	v_exp_f32_e32 v247, v247
	v_exp_f32_e32 v248, v248
	v_exp_f32_e32 v249, v249
	v_add_f32_e32 v242, 1.0, v242
	v_add_f32_e32 v243, 1.0, v243
	v_add_f32_e32 v244, 1.0, v244
	v_add_f32_e32 v245, 1.0, v245
	v_add_f32_e32 v246, 1.0, v246
	v_add_f32_e32 v247, 1.0, v247
	v_add_f32_e32 v248, 1.0, v248
	v_add_f32_e32 v249, 1.0, v249
	v_rcp_f32_e32 v242, v242
	v_rcp_f32_e32 v243, v243
	v_rcp_f32_e32 v244, v244
	v_rcp_f32_e32 v245, v245
	v_rcp_f32_e32 v246, v246
	v_rcp_f32_e32 v247, v247
	v_rcp_f32_e32 v248, v248
	v_rcp_f32_e32 v249, v249
	v_mul_f32_e32 v242, v234, v242
	v_mul_f32_e32 v243, v235, v243
	v_mul_f32_e32 v244, v236, v244
	v_mul_f32_e32 v245, v237, v245
	v_mul_f32_e32 v246, v238, v246
	v_mul_f32_e32 v247, v239, v247
	v_mul_f32_e32 v248, v240, v248
	v_mul_f32_e32 v249, v241, v249
	v_mul_f32_e32 v186, v186, v242
	v_mul_f32_e32 v187, v187, v243
	v_mul_f32_e32 v188, v188, v244
	v_mul_f32_e32 v189, v189, v245
	v_mul_f32_e32 v190, v190, v246
	v_mul_f32_e32 v191, v191, v247
	v_mul_f32_e32 v192, v192, v248
	v_mul_f32_e32 v193, v193, v249
	v_cvt_pk_bf16_f32 v44, v174, v175
	v_cvt_pk_bf16_f32 v45, v176, v177
	v_cvt_pk_bf16_f32 v60, v178, v179
	v_cvt_pk_bf16_f32 v61, v180, v181
	v_cvt_pk_bf16_f32 v56, v186, v187
	v_cvt_pk_bf16_f32 v57, v188, v189
	v_cvt_pk_bf16_f32 v40, v190, v191
	v_cvt_pk_bf16_f32 v41, v192, v193
	ds_read_b128 v[130:133], v213 offset:512
	ds_read_b128 v[134:137], v213 offset:576
	ds_read_b128 v[138:141], v213 offset:640
	ds_read_b128 v[142:145], v213 offset:704
	ds_read_b128 v[158:161], v213 offset:768
	ds_read_b128 v[162:165], v213 offset:832
	ds_read_b128 v[166:169], v213 offset:896
	ds_read_b128 v[170:173], v213 offset:960
	v_cndmask_b32_e64 v202, v72, v76, s[12:13]
	v_cndmask_b32_e64 v203, v73, v77, s[12:13]
	v_cndmask_b32_e64 v204, v74, v78, s[12:13]
	v_cndmask_b32_e64 v205, v75, v79, s[12:13]
	v_cndmask_b32_e64 v206, v68, v64, s[12:13]
	v_cndmask_b32_e64 v207, v69, v65, s[12:13]
	v_cndmask_b32_e64 v208, v70, v66, s[12:13]
	v_cndmask_b32_e64 v209, v71, v67, s[12:13]
	v_cvt_pk_bf16_f32 v250, v202, v203
	v_cvt_pk_bf16_f32 v251, v204, v205
	v_cvt_pk_bf16_f32 v252, v206, v207
	v_cvt_pk_bf16_f32 v253, v208, v209
	s_sub_u32 s10, s10, 0x16000
	s_subb_u32 s11, s11, 0
	s_mov_b64 s[42:43], exec
	s_and_b64 exec, exec, s[22:23]
	global_store_dwordx2 v195, v[250:251], s[10:11] offset:8
	global_store_dwordx2 v197, v[252:253], s[10:11] offset:8
	s_mov_b64 exec, s[42:43]
	s_waitcnt lgkmcnt(0)
; #define DPP_UP(v) __int_as_float(__builtin_amdgcn_update_dpp(0, __float_as_int(v), 0x121, 0xf, 0xf, false))
; #define DPP_DN(v) __int_as_float(__builtin_amdgcn_update_dpp(0, __float_as_int(v), 0x12F, 0xf, 0xf, false))
;     __device__ __forceinline__ void operator()(const f32x4 (&acc)[2][2][4][2], const Unit& u, int wr, int wc, int fr_in, int fq_in) const {
;     ...
;                     const f32x4 k0 = *(const f32x4*)(fk + co + ch), k1 = *(const f32x4*)(fk + DFF2 + co + ch), k2 = *(const f32x4*)(fk + 2 * DFF2 + co + ch), bb = *(const f32x4*)(fb + co + ch);
;                     f32x4 up_prev = (f32x4){0.f, 0.f, 0.f, 0.f}, up_cur, dn_cur, dn_next;
; #pragma unroll
;                     for (int j = 0; j < 4; ++j) dn_cur[j] = DPP_DN(acc[ai][pass][0][n][j]);
; #pragma unroll
;                     for (int m = 0; m < 4; ++m) {
;                         const f32x4 xv = acc[ai][pass][m][n];
; #pragma unroll
;                         for (int j = 0; j < 4; ++j) { up_cur[j] = DPP_UP(xv[j]); dn_next[j] = (m < 3) ? DPP_DN(acc[ai][pass][m < 3 ? m + 1 : 3][n][j]) : 0.f; }
;                         const f32x4 xp = f0 ? up_prev : up_cur, xn = f15 ? dn_next : dn_cur;
;                         const f32x4 c = (k0 * xp + k1 * xv) + (k2 * xn + bb);
;                         if (pass == 0) o[m] = c;
;                         else { f32x4 e;
; #pragma unroll
;                             for (int j = 0; j < 4; ++j) e[j] = __builtin_amdgcn_rcpf(1.0f + __builtin_amdgcn_exp2f(c[j] * -1.4426950408889634f));
;                             o[m] = o[m] * (c * e); }
;                         up_prev = up_cur; dn_cur = dn_next; }
	v_fma_f32 v174, v134, v76, v142
	v_fma_f32 v175, v135, v77, v143
	v_fma_f32 v176, v136, v78, v144
	v_fma_f32 v177, v137, v79, v145
	v_fma_f32 v178, v134, v92, v142
	v_fma_f32 v179, v135, v93, v143
	v_fma_f32 v180, v136, v94, v144
	v_fma_f32 v181, v137, v95, v145
	v_fma_f32 v186, v134, v88, v142
	v_fma_f32 v187, v135, v89, v143
	v_fma_f32 v188, v136, v90, v144
	v_fma_f32 v189, v137, v91, v145
	v_fma_f32 v190, v134, v72, v142
	v_fma_f32 v191, v135, v73, v143
	v_fma_f32 v192, v136, v74, v144
	v_fma_f32 v193, v137, v75, v145
	v_fmac_f32_dpp v174, v76, v130 row_shr:1 row_mask:0xf bank_mask:0xf
	v_fmac_f32_dpp v175, v77, v131 row_shr:1 row_mask:0xf bank_mask:0xf
	v_fmac_f32_dpp v176, v78, v132 row_shr:1 row_mask:0xf bank_mask:0xf
	v_fmac_f32_dpp v177, v79, v133 row_shr:1 row_mask:0xf bank_mask:0xf
	v_fmac_f32_dpp v174, v76, v138 row_shl:1 row_mask:0xf bank_mask:0xf
	v_fmac_f32_dpp v175, v77, v139 row_shl:1 row_mask:0xf bank_mask:0xf
	v_fmac_f32_dpp v176, v78, v140 row_shl:1 row_mask:0xf bank_mask:0xf
	v_fmac_f32_dpp v177, v79, v141 row_shl:1 row_mask:0xf bank_mask:0xf
	v_fmac_f32_dpp v174, v92, v138 row_shr:15 row_mask:0xf bank_mask:0xf
	v_fmac_f32_dpp v175, v93, v139 row_shr:15 row_mask:0xf bank_mask:0xf
	v_fmac_f32_dpp v176, v94, v140 row_shr:15 row_mask:0xf bank_mask:0xf
	v_fmac_f32_dpp v177, v95, v141 row_shr:15 row_mask:0xf bank_mask:0xf
	v_fmac_f32_dpp v178, v92, v130 row_shr:1 row_mask:0xf bank_mask:0xf
	v_fmac_f32_dpp v179, v93, v131 row_shr:1 row_mask:0xf bank_mask:0xf
	v_fmac_f32_dpp v180, v94, v132 row_shr:1 row_mask:0xf bank_mask:0xf
	v_fmac_f32_dpp v181, v95, v133 row_shr:1 row_mask:0xf bank_mask:0xf
	v_fmac_f32_dpp v178, v76, v130 row_shl:15 row_mask:0xf bank_mask:0xf
	v_fmac_f32_dpp v179, v77, v131 row_shl:15 row_mask:0xf bank_mask:0xf
	v_fmac_f32_dpp v180, v78, v132 row_shl:15 row_mask:0xf bank_mask:0xf
	v_fmac_f32_dpp v181, v79, v133 row_shl:15 row_mask:0xf bank_mask:0xf
	v_fmac_f32_dpp v178, v92, v138 row_shl:1 row_mask:0xf bank_mask:0xf
	v_fmac_f32_dpp v179, v93, v139 row_shl:1 row_mask:0xf bank_mask:0xf
	v_fmac_f32_dpp v180, v94, v140 row_shl:1 row_mask:0xf bank_mask:0xf
	v_fmac_f32_dpp v181, v95, v141 row_shl:1 row_mask:0xf bank_mask:0xf
	v_fmac_f32_dpp v178, v88, v138 row_shr:15 row_mask:0xf bank_mask:0xf
	v_fmac_f32_dpp v179, v89, v139 row_shr:15 row_mask:0xf bank_mask:0xf
	v_fmac_f32_dpp v180, v90, v140 row_shr:15 row_mask:0xf bank_mask:0xf
	v_fmac_f32_dpp v181, v91, v141 row_shr:15 row_mask:0xf bank_mask:0xf
	v_fmac_f32_dpp v186, v88, v130 row_shr:1 row_mask:0xf bank_mask:0xf
	v_fmac_f32_dpp v187, v89, v131 row_shr:1 row_mask:0xf bank_mask:0xf
	v_fmac_f32_dpp v188, v90, v132 row_shr:1 row_mask:0xf bank_mask:0xf
	v_fmac_f32_dpp v189, v91, v133 row_shr:1 row_mask:0xf bank_mask:0xf
	v_fmac_f32_dpp v186, v92, v130 row_shl:15 row_mask:0xf bank_mask:0xf
	v_fmac_f32_dpp v187, v93, v131 row_shl:15 row_mask:0xf bank_mask:0xf
	v_fmac_f32_dpp v188, v94, v132 row_shl:15 row_mask:0xf bank_mask:0xf
	v_fmac_f32_dpp v189, v95, v133 row_shl:15 row_mask:0xf bank_mask:0xf
	v_fmac_f32_dpp v186, v88, v138 row_shl:1 row_mask:0xf bank_mask:0xf
	v_fmac_f32_dpp v187, v89, v139 row_shl:1 row_mask:0xf bank_mask:0xf
	v_fmac_f32_dpp v188, v90, v140 row_shl:1 row_mask:0xf bank_mask:0xf
	v_fmac_f32_dpp v189, v91, v141 row_shl:1 row_mask:0xf bank_mask:0xf
	v_fmac_f32_dpp v186, v72, v138 row_shr:15 row_mask:0xf bank_mask:0xf
	v_fmac_f32_dpp v187, v73, v139 row_shr:15 row_mask:0xf bank_mask:0xf
	v_fmac_f32_dpp v188, v74, v140 row_shr:15 row_mask:0xf bank_mask:0xf
	v_fmac_f32_dpp v189, v75, v141 row_shr:15 row_mask:0xf bank_mask:0xf
	v_fmac_f32_dpp v190, v72, v130 row_shr:1 row_mask:0xf bank_mask:0xf
	v_fmac_f32_dpp v191, v73, v131 row_shr:1 row_mask:0xf bank_mask:0xf
	v_fmac_f32_dpp v192, v74, v132 row_shr:1 row_mask:0xf bank_mask:0xf
	v_fmac_f32_dpp v193, v75, v133 row_shr:1 row_mask:0xf bank_mask:0xf
	v_fmac_f32_dpp v190, v88, v130 row_shl:15 row_mask:0xf bank_mask:0xf
	v_fmac_f32_dpp v191, v89, v131 row_shl:15 row_mask:0xf bank_mask:0xf
	v_fmac_f32_dpp v192, v90, v132 row_shl:15 row_mask:0xf bank_mask:0xf
	v_fmac_f32_dpp v193, v91, v133 row_shl:15 row_mask:0xf bank_mask:0xf
	v_fmac_f32_dpp v190, v72, v138 row_shl:1 row_mask:0xf bank_mask:0xf
	v_fmac_f32_dpp v191, v73, v139 row_shl:1 row_mask:0xf bank_mask:0xf
	v_fmac_f32_dpp v192, v74, v140 row_shl:1 row_mask:0xf bank_mask:0xf
	v_fmac_f32_dpp v193, v75, v141 row_shl:1 row_mask:0xf bank_mask:0xf
	v_fma_f32 v226, v162, v64, v170
	v_fma_f32 v227, v163, v65, v171
	v_fma_f32 v228, v164, v66, v172
	v_fma_f32 v229, v165, v67, v173
	v_fma_f32 v230, v162, v84, v170
	v_fma_f32 v231, v163, v85, v171
	v_fma_f32 v232, v164, v86, v172
	v_fma_f32 v233, v165, v87, v173
	v_fma_f32 v234, v162, v80, v170
	v_fma_f32 v235, v163, v81, v171
	v_fma_f32 v236, v164, v82, v172
	v_fma_f32 v237, v165, v83, v173
	v_fma_f32 v238, v162, v68, v170
	v_fma_f32 v239, v163, v69, v171
	v_fma_f32 v240, v164, v70, v172
	v_fma_f32 v241, v165, v71, v173
	v_fmac_f32_dpp v226, v64, v158 row_shr:1 row_mask:0xf bank_mask:0xf
	v_fmac_f32_dpp v227, v65, v159 row_shr:1 row_mask:0xf bank_mask:0xf
	v_fmac_f32_dpp v228, v66, v160 row_shr:1 row_mask:0xf bank_mask:0xf
	v_fmac_f32_dpp v229, v67, v161 row_shr:1 row_mask:0xf bank_mask:0xf
	v_fmac_f32_dpp v226, v64, v166 row_shl:1 row_mask:0xf bank_mask:0xf
	v_fmac_f32_dpp v227, v65, v167 row_shl:1 row_mask:0xf bank_mask:0xf
	v_fmac_f32_dpp v228, v66, v168 row_shl:1 row_mask:0xf bank_mask:0xf
	v_fmac_f32_dpp v229, v67, v169 row_shl:1 row_mask:0xf bank_mask:0xf
	v_fmac_f32_dpp v226, v84, v166 row_shr:15 row_mask:0xf bank_mask:0xf
	v_fmac_f32_dpp v227, v85, v167 row_shr:15 row_mask:0xf bank_mask:0xf
; #define DPP_UP(v) __int_as_float(__builtin_amdgcn_update_dpp(0, __float_as_int(v), 0x121, 0xf, 0xf, false))
; #define DPP_DN(v) __int_as_float(__builtin_amdgcn_update_dpp(0, __float_as_int(v), 0x12F, 0xf, 0xf, false))
;     __device__ __forceinline__ void operator()(const f32x4 (&acc)[2][2][4][2], const Unit& u, int wr, int wc, int fr_in, int fq_in) const {
;     ...
;                     const f32x4 k0 = *(const f32x4*)(fk + co + ch), k1 = *(const f32x4*)(fk + DFF2 + co + ch), k2 = *(const f32x4*)(fk + 2 * DFF2 + co + ch), bb = *(const f32x4*)(fb + co + ch);
;                     f32x4 up_prev = (f32x4){0.f, 0.f, 0.f, 0.f}, up_cur, dn_cur, dn_next;
; #pragma unroll
;                     for (int j = 0; j < 4; ++j) dn_cur[j] = DPP_DN(acc[ai][pass][0][n][j]);
; #pragma unroll
;                     for (int m = 0; m < 4; ++m) {
;                         const f32x4 xv = acc[ai][pass][m][n];
; #pragma unroll
;                         for (int j = 0; j < 4; ++j) { up_cur[j] = DPP_UP(xv[j]); dn_next[j] = (m < 3) ? DPP_DN(acc[ai][pass][m < 3 ? m + 1 : 3][n][j]) : 0.f; }
;                         const f32x4 xp = f0 ? up_prev : up_cur, xn = f15 ? dn_next : dn_cur;
;                         const f32x4 c = (k0 * xp + k1 * xv) + (k2 * xn + bb);
;                         if (pass == 0) o[m] = c;
;                         else { f32x4 e;
; #pragma unroll
;                             for (int j = 0; j < 4; ++j) e[j] = __builtin_amdgcn_rcpf(1.0f + __builtin_amdgcn_exp2f(c[j] * -1.4426950408889634f));
;                             o[m] = o[m] * (c * e); }
	v_fmac_f32_dpp v228, v86, v168 row_shr:15 row_mask:0xf bank_mask:0xf
	v_fmac_f32_dpp v229, v87, v169 row_shr:15 row_mask:0xf bank_mask:0xf
	v_fmac_f32_dpp v230, v84, v158 row_shr:1 row_mask:0xf bank_mask:0xf
	v_fmac_f32_dpp v231, v85, v159 row_shr:1 row_mask:0xf bank_mask:0xf
	v_fmac_f32_dpp v232, v86, v160 row_shr:1 row_mask:0xf bank_mask:0xf
	v_fmac_f32_dpp v233, v87, v161 row_shr:1 row_mask:0xf bank_mask:0xf
	v_fmac_f32_dpp v230, v64, v158 row_shl:15 row_mask:0xf bank_mask:0xf
	v_fmac_f32_dpp v231, v65, v159 row_shl:15 row_mask:0xf bank_mask:0xf
	v_fmac_f32_dpp v232, v66, v160 row_shl:15 row_mask:0xf bank_mask:0xf
	v_fmac_f32_dpp v233, v67, v161 row_shl:15 row_mask:0xf bank_mask:0xf
	v_fmac_f32_dpp v230, v84, v166 row_shl:1 row_mask:0xf bank_mask:0xf
	v_fmac_f32_dpp v231, v85, v167 row_shl:1 row_mask:0xf bank_mask:0xf
	v_fmac_f32_dpp v232, v86, v168 row_shl:1 row_mask:0xf bank_mask:0xf
	v_fmac_f32_dpp v233, v87, v169 row_shl:1 row_mask:0xf bank_mask:0xf
	v_fmac_f32_dpp v230, v80, v166 row_shr:15 row_mask:0xf bank_mask:0xf
	v_fmac_f32_dpp v231, v81, v167 row_shr:15 row_mask:0xf bank_mask:0xf
	v_fmac_f32_dpp v232, v82, v168 row_shr:15 row_mask:0xf bank_mask:0xf
	v_fmac_f32_dpp v233, v83, v169 row_shr:15 row_mask:0xf bank_mask:0xf
	v_fmac_f32_dpp v234, v80, v158 row_shr:1 row_mask:0xf bank_mask:0xf
	v_fmac_f32_dpp v235, v81, v159 row_shr:1 row_mask:0xf bank_mask:0xf
	v_fmac_f32_dpp v236, v82, v160 row_shr:1 row_mask:0xf bank_mask:0xf
	v_fmac_f32_dpp v237, v83, v161 row_shr:1 row_mask:0xf bank_mask:0xf
	v_fmac_f32_dpp v234, v84, v158 row_shl:15 row_mask:0xf bank_mask:0xf
	v_fmac_f32_dpp v235, v85, v159 row_shl:15 row_mask:0xf bank_mask:0xf
	v_fmac_f32_dpp v236, v86, v160 row_shl:15 row_mask:0xf bank_mask:0xf
	v_fmac_f32_dpp v237, v87, v161 row_shl:15 row_mask:0xf bank_mask:0xf
	v_fmac_f32_dpp v234, v80, v166 row_shl:1 row_mask:0xf bank_mask:0xf
	v_fmac_f32_dpp v235, v81, v167 row_shl:1 row_mask:0xf bank_mask:0xf
	v_fmac_f32_dpp v236, v82, v168 row_shl:1 row_mask:0xf bank_mask:0xf
	v_fmac_f32_dpp v237, v83, v169 row_shl:1 row_mask:0xf bank_mask:0xf
	v_fmac_f32_dpp v234, v68, v166 row_shr:15 row_mask:0xf bank_mask:0xf
	v_fmac_f32_dpp v235, v69, v167 row_shr:15 row_mask:0xf bank_mask:0xf
	v_fmac_f32_dpp v236, v70, v168 row_shr:15 row_mask:0xf bank_mask:0xf
	v_fmac_f32_dpp v237, v71, v169 row_shr:15 row_mask:0xf bank_mask:0xf
	v_fmac_f32_dpp v238, v68, v158 row_shr:1 row_mask:0xf bank_mask:0xf
	v_fmac_f32_dpp v239, v69, v159 row_shr:1 row_mask:0xf bank_mask:0xf
	v_fmac_f32_dpp v240, v70, v160 row_shr:1 row_mask:0xf bank_mask:0xf
	v_fmac_f32_dpp v241, v71, v161 row_shr:1 row_mask:0xf bank_mask:0xf
	v_fmac_f32_dpp v238, v80, v158 row_shl:15 row_mask:0xf bank_mask:0xf
	v_fmac_f32_dpp v239, v81, v159 row_shl:15 row_mask:0xf bank_mask:0xf
	v_fmac_f32_dpp v240, v82, v160 row_shl:15 row_mask:0xf bank_mask:0xf
	v_fmac_f32_dpp v241, v83, v161 row_shl:15 row_mask:0xf bank_mask:0xf
	v_fmac_f32_dpp v238, v68, v166 row_shl:1 row_mask:0xf bank_mask:0xf
	v_fmac_f32_dpp v239, v69, v167 row_shl:1 row_mask:0xf bank_mask:0xf
	v_fmac_f32_dpp v240, v70, v168 row_shl:1 row_mask:0xf bank_mask:0xf
	v_fmac_f32_dpp v241, v71, v169 row_shl:1 row_mask:0xf bank_mask:0xf
	v_mul_f32_e32 v242, 0xbfb8aa3b, v226
	v_mul_f32_e32 v243, 0xbfb8aa3b, v227
	v_mul_f32_e32 v244, 0xbfb8aa3b, v228
	v_mul_f32_e32 v245, 0xbfb8aa3b, v229
	v_mul_f32_e32 v246, 0xbfb8aa3b, v230
	v_mul_f32_e32 v247, 0xbfb8aa3b, v231
	v_mul_f32_e32 v248, 0xbfb8aa3b, v232
	v_mul_f32_e32 v249, 0xbfb8aa3b, v233
	v_exp_f32_e32 v242, v242
	v_exp_f32_e32 v243, v243
	v_exp_f32_e32 v244, v244
	v_exp_f32_e32 v245, v245
	v_exp_f32_e32 v246, v246
	v_exp_f32_e32 v247, v247
	v_exp_f32_e32 v248, v248
	v_exp_f32_e32 v249, v249
	v_add_f32_e32 v242, 1.0, v242
	v_add_f32_e32 v243, 1.0, v243
	v_add_f32_e32 v244, 1.0, v244
	v_add_f32_e32 v245, 1.0, v245
	v_add_f32_e32 v246, 1.0, v246
	v_add_f32_e32 v247, 1.0, v247
	v_add_f32_e32 v248, 1.0, v248
	v_add_f32_e32 v249, 1.0, v249
	v_rcp_f32_e32 v242, v242
	v_rcp_f32_e32 v243, v243
	v_rcp_f32_e32 v244, v244
	v_rcp_f32_e32 v245, v245
	v_rcp_f32_e32 v246, v246
	v_rcp_f32_e32 v247, v247
	v_rcp_f32_e32 v248, v248
	v_rcp_f32_e32 v249, v249
	v_mul_f32_e32 v242, v226, v242
	v_mul_f32_e32 v243, v227, v243
	v_mul_f32_e32 v244, v228, v244
	v_mul_f32_e32 v245, v229, v245
	v_mul_f32_e32 v246, v230, v246
	v_mul_f32_e32 v247, v231, v247
	v_mul_f32_e32 v248, v232, v248
	v_mul_f32_e32 v249, v233, v249
	v_mul_f32_e32 v174, v174, v242
	v_mul_f32_e32 v175, v175, v243
	v_mul_f32_e32 v176, v176, v244
	v_mul_f32_e32 v177, v177, v245
	v_mul_f32_e32 v178, v178, v246
	v_mul_f32_e32 v179, v179, v247
	v_mul_f32_e32 v180, v180, v248
	v_mul_f32_e32 v181, v181, v249
	v_mul_f32_e32 v242, 0xbfb8aa3b, v234
	v_mul_f32_e32 v243, 0xbfb8aa3b, v235
	v_mul_f32_e32 v244, 0xbfb8aa3b, v236
	v_mul_f32_e32 v245, 0xbfb8aa3b, v237
	v_mul_f32_e32 v246, 0xbfb8aa3b, v238
	v_mul_f32_e32 v247, 0xbfb8aa3b, v239
	v_mul_f32_e32 v248, 0xbfb8aa3b, v240
	v_mul_f32_e32 v249, 0xbfb8aa3b, v241
	v_exp_f32_e32 v242, v242
	v_exp_f32_e32 v243, v243
	v_exp_f32_e32 v244, v244
	v_exp_f32_e32 v245, v245
	v_exp_f32_e32 v246, v246
	v_exp_f32_e32 v247, v247
	v_exp_f32_e32 v248, v248
	v_exp_f32_e32 v249, v249
	v_add_f32_e32 v242, 1.0, v242
	v_add_f32_e32 v243, 1.0, v243
	v_add_f32_e32 v244, 1.0, v244
	v_add_f32_e32 v245, 1.0, v245
	v_add_f32_e32 v246, 1.0, v246
	v_add_f32_e32 v247, 1.0, v247
	v_add_f32_e32 v248, 1.0, v248
	v_add_f32_e32 v249, 1.0, v249
	v_rcp_f32_e32 v242, v242
	v_rcp_f32_e32 v243, v243
	v_rcp_f32_e32 v244, v244
	v_rcp_f32_e32 v245, v245
	v_rcp_f32_e32 v246, v246
	v_rcp_f32_e32 v247, v247
	v_rcp_f32_e32 v248, v248
	v_rcp_f32_e32 v249, v249
; __device__ __forceinline__ unsigned cvt_pk_bf16(float lo, float hi) { unsigned r; asm volatile("v_cvt_pk_bf16_f32 %0, %1, %2" : "=v"(r) : "v"(lo), "v"(hi)); return r; }
;     __device__ __forceinline__ void operator()(const f32x4 (&acc)[2][2][4][2], const Unit& u, int wr, int wc, int fr_in, int fq_in) const {
;     ...
;                         else { f32x4 e;
; #pragma unroll
;                             for (int j = 0; j < 4; ++j) e[j] = __builtin_amdgcn_rcpf(1.0f + __builtin_amdgcn_exp2f(c[j] * -1.4426950408889634f));
;                             o[m] = o[m] * (c * e); }
;                         up_prev = up_cur; dn_cur = dn_next; }
;                 }
;                 if (n == 0) {
; #pragma unroll
;                     for (int m = 0; m < 4; ++m) { wlo[m].x = cvt_pk_bf16(o[m][0], o[m][1]); wlo[m].y = cvt_pk_bf16(o[m][2], o[m][3]); }
;                 } else {
; #pragma unroll
;                     for (int m = 0; m < 4; ++m) { u32x4 w; w.x = wlo[m].x; w.y = wlo[m].y; w.z = cvt_pk_bf16(o[m][0], o[m][1]); w.w = cvt_pk_bf16(o[m][2], o[m][3]);
;                         *(u32x4*)(base + off0 + (unsigned)(ai * HALF + m * 16) * (DFF * 2u)) = w; }
;                 }
;                 if (fr < 2 || fr >= 14) { const int k = fr < 2 ? fr : fr - 12;
;                     const f32x4 xv = fr < 2 ? acc[ai][0][0][n] : acc[ai][0][3][n], yv = fr < 2 ? acc[ai][1][0][n] : acc[ai][1][3][n];
;                     char* sp = sbase + (size_t)((2 * ai + wr) * 4 + k) * (DFF2 * 2) + (size_t)ch * 2;
;                     u32x2 a, b; a.x = cvt_pk_bf16(xv[0], xv[1]); a.y = cvt_pk_bf16(xv[2], xv[3]); b.x = cvt_pk_bf16(yv[0], yv[1]); b.y = cvt_pk_bf16(yv[2], yv[3]);
;                     *(u32x2*)sp = a; *(u32x2*)(sp + DFF * 2) = b; }
	v_mul_f32_e32 v242, v234, v242
	v_mul_f32_e32 v243, v235, v243
	v_mul_f32_e32 v244, v236, v244
	v_mul_f32_e32 v245, v237, v245
	v_mul_f32_e32 v246, v238, v246
	v_mul_f32_e32 v247, v239, v247
	v_mul_f32_e32 v248, v240, v248
	v_mul_f32_e32 v249, v241, v249
	v_mul_f32_e32 v186, v186, v242
	v_mul_f32_e32 v187, v187, v243
	v_mul_f32_e32 v188, v188, v244
	v_mul_f32_e32 v189, v189, v245
	v_mul_f32_e32 v190, v190, v246
	v_mul_f32_e32 v191, v191, v247
	v_mul_f32_e32 v192, v192, v248
	v_mul_f32_e32 v193, v193, v249
	v_cvt_pk_bf16_f32 v112, v174, v175
	v_cvt_pk_bf16_f32 v113, v176, v177
	v_cvt_pk_bf16_f32 v128, v178, v179
	v_cvt_pk_bf16_f32 v129, v180, v181
	v_cvt_pk_bf16_f32 v124, v186, v187
	v_cvt_pk_bf16_f32 v125, v188, v189
	v_cvt_pk_bf16_f32 v108, v190, v191
	v_cvt_pk_bf16_f32 v109, v192, v193
	global_store_dwordx4 v194, v[110:113], s[6:7]
	s_add_u32 s0, s6, 0x16000
	s_addc_u32 s1, s7, 0
	global_store_dwordx4 v194, v[126:129], s[0:1]
	s_add_u32 s0, s6, 0x2c000
	s_addc_u32 s1, s7, 0
	global_store_dwordx4 v194, v[122:125], s[0:1]
	s_add_u32 s0, s6, 0x42000
	s_addc_u32 s1, s7, 0
	global_store_dwordx4 v194, v[106:109], s[0:1]
	v_cndmask_b32_e64 v202, v4, v0, s[12:13]
	v_cndmask_b32_e64 v203, v5, v1, s[12:13]
	v_cndmask_b32_e64 v204, v6, v2, s[12:13]
	v_cndmask_b32_e64 v205, v7, v3, s[12:13]
	v_cndmask_b32_e64 v206, v12, v8, s[12:13]
	v_cndmask_b32_e64 v207, v13, v9, s[12:13]
	v_cndmask_b32_e64 v208, v14, v10, s[12:13]
	v_cndmask_b32_e64 v209, v15, v11, s[12:13]
	v_cvt_pk_bf16_f32 v250, v202, v203
	v_cvt_pk_bf16_f32 v251, v204, v205
	v_cvt_pk_bf16_f32 v252, v206, v207
	v_cvt_pk_bf16_f32 v253, v208, v209
	s_add_u32 s10, s10, 0x16000
	s_addc_u32 s11, s11, 0
	s_mov_b64 s[42:43], exec
	s_and_b64 exec, exec, s[22:23]
	global_store_dwordx2 v195, v[250:251], s[10:11] offset:8
	global_store_dwordx2 v197, v[252:253], s[10:11] offset:8
	s_mov_b64 exec, s[42:43]
	v_fma_f32 v174, v134, v0, v142
	v_fma_f32 v175, v135, v1, v143
	v_fma_f32 v176, v136, v2, v144
	v_fma_f32 v177, v137, v3, v145
	v_fma_f32 v178, v134, v28, v142
	v_fma_f32 v179, v135, v29, v143
	v_fma_f32 v180, v136, v30, v144
	v_fma_f32 v181, v137, v31, v145
	v_fma_f32 v186, v134, v24, v142
	v_fma_f32 v187, v135, v25, v143
	v_fma_f32 v188, v136, v26, v144
	v_fma_f32 v189, v137, v27, v145
	v_fma_f32 v190, v134, v4, v142
	v_fma_f32 v191, v135, v5, v143
	v_fma_f32 v192, v136, v6, v144
	v_fma_f32 v193, v137, v7, v145
	v_fmac_f32_dpp v174, v0, v130 row_shr:1 row_mask:0xf bank_mask:0xf
	v_fmac_f32_dpp v175, v1, v131 row_shr:1 row_mask:0xf bank_mask:0xf
	v_fmac_f32_dpp v176, v2, v132 row_shr:1 row_mask:0xf bank_mask:0xf
	v_fmac_f32_dpp v177, v3, v133 row_shr:1 row_mask:0xf bank_mask:0xf
	v_fmac_f32_dpp v174, v0, v138 row_shl:1 row_mask:0xf bank_mask:0xf
	v_fmac_f32_dpp v175, v1, v139 row_shl:1 row_mask:0xf bank_mask:0xf
	v_fmac_f32_dpp v176, v2, v140 row_shl:1 row_mask:0xf bank_mask:0xf
	v_fmac_f32_dpp v177, v3, v141 row_shl:1 row_mask:0xf bank_mask:0xf
	v_fmac_f32_dpp v174, v28, v138 row_shr:15 row_mask:0xf bank_mask:0xf
	v_fmac_f32_dpp v175, v29, v139 row_shr:15 row_mask:0xf bank_mask:0xf
	v_fmac_f32_dpp v176, v30, v140 row_shr:15 row_mask:0xf bank_mask:0xf
	v_fmac_f32_dpp v177, v31, v141 row_shr:15 row_mask:0xf bank_mask:0xf
	v_fmac_f32_dpp v178, v28, v130 row_shr:1 row_mask:0xf bank_mask:0xf
	v_fmac_f32_dpp v179, v29, v131 row_shr:1 row_mask:0xf bank_mask:0xf
	v_fmac_f32_dpp v180, v30, v132 row_shr:1 row_mask:0xf bank_mask:0xf
	v_fmac_f32_dpp v181, v31, v133 row_shr:1 row_mask:0xf bank_mask:0xf
	v_fmac_f32_dpp v178, v0, v130 row_shl:15 row_mask:0xf bank_mask:0xf
	v_fmac_f32_dpp v179, v1, v131 row_shl:15 row_mask:0xf bank_mask:0xf
	v_fmac_f32_dpp v180, v2, v132 row_shl:15 row_mask:0xf bank_mask:0xf
	v_fmac_f32_dpp v181, v3, v133 row_shl:15 row_mask:0xf bank_mask:0xf
	v_fmac_f32_dpp v178, v28, v138 row_shl:1 row_mask:0xf bank_mask:0xf
	v_fmac_f32_dpp v179, v29, v139 row_shl:1 row_mask:0xf bank_mask:0xf
	v_fmac_f32_dpp v180, v30, v140 row_shl:1 row_mask:0xf bank_mask:0xf
	v_fmac_f32_dpp v181, v31, v141 row_shl:1 row_mask:0xf bank_mask:0xf
	v_fmac_f32_dpp v178, v24, v138 row_shr:15 row_mask:0xf bank_mask:0xf
	v_fmac_f32_dpp v179, v25, v139 row_shr:15 row_mask:0xf bank_mask:0xf
	v_fmac_f32_dpp v180, v26, v140 row_shr:15 row_mask:0xf bank_mask:0xf
	v_fmac_f32_dpp v181, v27, v141 row_shr:15 row_mask:0xf bank_mask:0xf
	v_fmac_f32_dpp v186, v24, v130 row_shr:1 row_mask:0xf bank_mask:0xf
	v_fmac_f32_dpp v187, v25, v131 row_shr:1 row_mask:0xf bank_mask:0xf
	v_fmac_f32_dpp v188, v26, v132 row_shr:1 row_mask:0xf bank_mask:0xf
	v_fmac_f32_dpp v189, v27, v133 row_shr:1 row_mask:0xf bank_mask:0xf
	v_fmac_f32_dpp v186, v28, v130 row_shl:15 row_mask:0xf bank_mask:0xf
	v_fmac_f32_dpp v187, v29, v131 row_shl:15 row_mask:0xf bank_mask:0xf
	v_fmac_f32_dpp v188, v30, v132 row_shl:15 row_mask:0xf bank_mask:0xf
	v_fmac_f32_dpp v189, v31, v133 row_shl:15 row_mask:0xf bank_mask:0xf
	v_fmac_f32_dpp v186, v24, v138 row_shl:1 row_mask:0xf bank_mask:0xf
	v_fmac_f32_dpp v187, v25, v139 row_shl:1 row_mask:0xf bank_mask:0xf
	v_fmac_f32_dpp v188, v26, v140 row_shl:1 row_mask:0xf bank_mask:0xf
	v_fmac_f32_dpp v189, v27, v141 row_shl:1 row_mask:0xf bank_mask:0xf
	v_fmac_f32_dpp v186, v4, v138 row_shr:15 row_mask:0xf bank_mask:0xf
	v_fmac_f32_dpp v187, v5, v139 row_shr:15 row_mask:0xf bank_mask:0xf
	v_fmac_f32_dpp v188, v6, v140 row_shr:15 row_mask:0xf bank_mask:0xf
	v_fmac_f32_dpp v189, v7, v141 row_shr:15 row_mask:0xf bank_mask:0xf
	v_fmac_f32_dpp v190, v4, v130 row_shr:1 row_mask:0xf bank_mask:0xf
	v_fmac_f32_dpp v191, v5, v131 row_shr:1 row_mask:0xf bank_mask:0xf
	v_fmac_f32_dpp v192, v6, v132 row_shr:1 row_mask:0xf bank_mask:0xf
; #define DPP_UP(v) __int_as_float(__builtin_amdgcn_update_dpp(0, __float_as_int(v), 0x121, 0xf, 0xf, false))
; #define DPP_DN(v) __int_as_float(__builtin_amdgcn_update_dpp(0, __float_as_int(v), 0x12F, 0xf, 0xf, false))
;     __device__ __forceinline__ void operator()(const f32x4 (&acc)[2][2][4][2], const Unit& u, int wr, int wc, int fr_in, int fq_in) const {
;     ...
;                     const f32x4 k0 = *(const f32x4*)(fk + co + ch), k1 = *(const f32x4*)(fk + DFF2 + co + ch), k2 = *(const f32x4*)(fk + 2 * DFF2 + co + ch), bb = *(const f32x4*)(fb + co + ch);
;                     f32x4 up_prev = (f32x4){0.f, 0.f, 0.f, 0.f}, up_cur, dn_cur, dn_next;
; #pragma unroll
;                     for (int j = 0; j < 4; ++j) dn_cur[j] = DPP_DN(acc[ai][pass][0][n][j]);
; #pragma unroll
;                     for (int m = 0; m < 4; ++m) {
;                         const f32x4 xv = acc[ai][pass][m][n];
; #pragma unroll
;                         for (int j = 0; j < 4; ++j) { up_cur[j] = DPP_UP(xv[j]); dn_next[j] = (m < 3) ? DPP_DN(acc[ai][pass][m < 3 ? m + 1 : 3][n][j]) : 0.f; }
;                         const f32x4 xp = f0 ? up_prev : up_cur, xn = f15 ? dn_next : dn_cur;
;                         const f32x4 c = (k0 * xp + k1 * xv) + (k2 * xn + bb);
;                         if (pass == 0) o[m] = c;
;                         else { f32x4 e;
; #pragma unroll
;                             for (int j = 0; j < 4; ++j) e[j] = __builtin_amdgcn_rcpf(1.0f + __builtin_amdgcn_exp2f(c[j] * -1.4426950408889634f));
;                             o[m] = o[m] * (c * e); }
;                         up_prev = up_cur; dn_cur = dn_next; }
	v_fmac_f32_dpp v193, v7, v133 row_shr:1 row_mask:0xf bank_mask:0xf
	v_fmac_f32_dpp v190, v24, v130 row_shl:15 row_mask:0xf bank_mask:0xf
	v_fmac_f32_dpp v191, v25, v131 row_shl:15 row_mask:0xf bank_mask:0xf
	v_fmac_f32_dpp v192, v26, v132 row_shl:15 row_mask:0xf bank_mask:0xf
	v_fmac_f32_dpp v193, v27, v133 row_shl:15 row_mask:0xf bank_mask:0xf
	v_fmac_f32_dpp v190, v4, v138 row_shl:1 row_mask:0xf bank_mask:0xf
	v_fmac_f32_dpp v191, v5, v139 row_shl:1 row_mask:0xf bank_mask:0xf
	v_fmac_f32_dpp v192, v6, v140 row_shl:1 row_mask:0xf bank_mask:0xf
	v_fmac_f32_dpp v193, v7, v141 row_shl:1 row_mask:0xf bank_mask:0xf
	v_fma_f32 v226, v162, v8, v170
	v_fma_f32 v227, v163, v9, v171
	v_fma_f32 v228, v164, v10, v172
	v_fma_f32 v229, v165, v11, v173
	v_fma_f32 v230, v162, v20, v170
	v_fma_f32 v231, v163, v21, v171
	v_fma_f32 v232, v164, v22, v172
	v_fma_f32 v233, v165, v23, v173
	v_fma_f32 v234, v162, v16, v170
	v_fma_f32 v235, v163, v17, v171
	v_fma_f32 v236, v164, v18, v172
	v_fma_f32 v237, v165, v19, v173
	v_fma_f32 v238, v162, v12, v170
	v_fma_f32 v239, v163, v13, v171
	v_fma_f32 v240, v164, v14, v172
	v_fma_f32 v241, v165, v15, v173
	v_fmac_f32_dpp v226, v8, v158 row_shr:1 row_mask:0xf bank_mask:0xf
	v_fmac_f32_dpp v227, v9, v159 row_shr:1 row_mask:0xf bank_mask:0xf
	v_fmac_f32_dpp v228, v10, v160 row_shr:1 row_mask:0xf bank_mask:0xf
	v_fmac_f32_dpp v229, v11, v161 row_shr:1 row_mask:0xf bank_mask:0xf
	v_fmac_f32_dpp v226, v8, v166 row_shl:1 row_mask:0xf bank_mask:0xf
	v_fmac_f32_dpp v227, v9, v167 row_shl:1 row_mask:0xf bank_mask:0xf
	v_fmac_f32_dpp v228, v10, v168 row_shl:1 row_mask:0xf bank_mask:0xf
	v_fmac_f32_dpp v229, v11, v169 row_shl:1 row_mask:0xf bank_mask:0xf
	v_fmac_f32_dpp v226, v20, v166 row_shr:15 row_mask:0xf bank_mask:0xf
	v_fmac_f32_dpp v227, v21, v167 row_shr:15 row_mask:0xf bank_mask:0xf
	v_fmac_f32_dpp v228, v22, v168 row_shr:15 row_mask:0xf bank_mask:0xf
	v_fmac_f32_dpp v229, v23, v169 row_shr:15 row_mask:0xf bank_mask:0xf
	v_fmac_f32_dpp v230, v20, v158 row_shr:1 row_mask:0xf bank_mask:0xf
	v_fmac_f32_dpp v231, v21, v159 row_shr:1 row_mask:0xf bank_mask:0xf
	v_fmac_f32_dpp v232, v22, v160 row_shr:1 row_mask:0xf bank_mask:0xf
	v_fmac_f32_dpp v233, v23, v161 row_shr:1 row_mask:0xf bank_mask:0xf
	v_fmac_f32_dpp v230, v8, v158 row_shl:15 row_mask:0xf bank_mask:0xf
	v_fmac_f32_dpp v231, v9, v159 row_shl:15 row_mask:0xf bank_mask:0xf
	v_fmac_f32_dpp v232, v10, v160 row_shl:15 row_mask:0xf bank_mask:0xf
	v_fmac_f32_dpp v233, v11, v161 row_shl:15 row_mask:0xf bank_mask:0xf
	v_fmac_f32_dpp v230, v20, v166 row_shl:1 row_mask:0xf bank_mask:0xf
	v_fmac_f32_dpp v231, v21, v167 row_shl:1 row_mask:0xf bank_mask:0xf
	v_fmac_f32_dpp v232, v22, v168 row_shl:1 row_mask:0xf bank_mask:0xf
	v_fmac_f32_dpp v233, v23, v169 row_shl:1 row_mask:0xf bank_mask:0xf
	v_fmac_f32_dpp v230, v16, v166 row_shr:15 row_mask:0xf bank_mask:0xf
	v_fmac_f32_dpp v231, v17, v167 row_shr:15 row_mask:0xf bank_mask:0xf
	v_fmac_f32_dpp v232, v18, v168 row_shr:15 row_mask:0xf bank_mask:0xf
	v_fmac_f32_dpp v233, v19, v169 row_shr:15 row_mask:0xf bank_mask:0xf
	v_fmac_f32_dpp v234, v16, v158 row_shr:1 row_mask:0xf bank_mask:0xf
	v_fmac_f32_dpp v235, v17, v159 row_shr:1 row_mask:0xf bank_mask:0xf
	v_fmac_f32_dpp v236, v18, v160 row_shr:1 row_mask:0xf bank_mask:0xf
	v_fmac_f32_dpp v237, v19, v161 row_shr:1 row_mask:0xf bank_mask:0xf
	v_fmac_f32_dpp v234, v20, v158 row_shl:15 row_mask:0xf bank_mask:0xf
	v_fmac_f32_dpp v235, v21, v159 row_shl:15 row_mask:0xf bank_mask:0xf
	v_fmac_f32_dpp v236, v22, v160 row_shl:15 row_mask:0xf bank_mask:0xf
	v_fmac_f32_dpp v237, v23, v161 row_shl:15 row_mask:0xf bank_mask:0xf
	v_fmac_f32_dpp v234, v16, v166 row_shl:1 row_mask:0xf bank_mask:0xf
	v_fmac_f32_dpp v235, v17, v167 row_shl:1 row_mask:0xf bank_mask:0xf
	v_fmac_f32_dpp v236, v18, v168 row_shl:1 row_mask:0xf bank_mask:0xf
	v_fmac_f32_dpp v237, v19, v169 row_shl:1 row_mask:0xf bank_mask:0xf
	v_fmac_f32_dpp v234, v12, v166 row_shr:15 row_mask:0xf bank_mask:0xf
	v_fmac_f32_dpp v235, v13, v167 row_shr:15 row_mask:0xf bank_mask:0xf
	v_fmac_f32_dpp v236, v14, v168 row_shr:15 row_mask:0xf bank_mask:0xf
	v_fmac_f32_dpp v237, v15, v169 row_shr:15 row_mask:0xf bank_mask:0xf
	v_fmac_f32_dpp v238, v12, v158 row_shr:1 row_mask:0xf bank_mask:0xf
	v_fmac_f32_dpp v239, v13, v159 row_shr:1 row_mask:0xf bank_mask:0xf
; __device__ __forceinline__ unsigned cvt_pk_bf16(float lo, float hi) { unsigned r; asm volatile("v_cvt_pk_bf16_f32 %0, %1, %2" : "=v"(r) : "v"(lo), "v"(hi)); return r; }
; #define DPP_UP(v) __int_as_float(__builtin_amdgcn_update_dpp(0, __float_as_int(v), 0x121, 0xf, 0xf, false))
; #define DPP_DN(v) __int_as_float(__builtin_amdgcn_update_dpp(0, __float_as_int(v), 0x12F, 0xf, 0xf, false))
;     __device__ __forceinline__ void operator()(const f32x4 (&acc)[2][2][4][2], const Unit& u, int wr, int wc, int fr_in, int fq_in) const {
;     ...
;                     const f32x4 k0 = *(const f32x4*)(fk + co + ch), k1 = *(const f32x4*)(fk + DFF2 + co + ch), k2 = *(const f32x4*)(fk + 2 * DFF2 + co + ch), bb = *(const f32x4*)(fb + co + ch);
;                     f32x4 up_prev = (f32x4){0.f, 0.f, 0.f, 0.f}, up_cur, dn_cur, dn_next;
; #pragma unroll
;                     for (int j = 0; j < 4; ++j) dn_cur[j] = DPP_DN(acc[ai][pass][0][n][j]);
; #pragma unroll
;                     for (int m = 0; m < 4; ++m) {
;                         const f32x4 xv = acc[ai][pass][m][n];
; #pragma unroll
;                         for (int j = 0; j < 4; ++j) { up_cur[j] = DPP_UP(xv[j]); dn_next[j] = (m < 3) ? DPP_DN(acc[ai][pass][m < 3 ? m + 1 : 3][n][j]) : 0.f; }
;                         const f32x4 xp = f0 ? up_prev : up_cur, xn = f15 ? dn_next : dn_cur;
;                         const f32x4 c = (k0 * xp + k1 * xv) + (k2 * xn + bb);
;                         if (pass == 0) o[m] = c;
;                         else { f32x4 e;
; #pragma unroll
;                             for (int j = 0; j < 4; ++j) e[j] = __builtin_amdgcn_rcpf(1.0f + __builtin_amdgcn_exp2f(c[j] * -1.4426950408889634f));
;                             o[m] = o[m] * (c * e); }
;                         up_prev = up_cur; dn_cur = dn_next; }
;                 }
;                 if (n == 0) {
; #pragma unroll
;                     for (int m = 0; m < 4; ++m) { wlo[m].x = cvt_pk_bf16(o[m][0], o[m][1]); wlo[m].y = cvt_pk_bf16(o[m][2], o[m][3]); }
;                 } else {
; #pragma unroll
;                     for (int m = 0; m < 4; ++m) { u32x4 w; w.x = wlo[m].x; w.y = wlo[m].y; w.z = cvt_pk_bf16(o[m][0], o[m][1]); w.w = cvt_pk_bf16(o[m][2], o[m][3]);
;                         *(u32x4*)(base + off0 + (unsigned)(ai * HALF + m * 16) * (DFF * 2u)) = w; }
	v_fmac_f32_dpp v240, v14, v160 row_shr:1 row_mask:0xf bank_mask:0xf
	v_fmac_f32_dpp v241, v15, v161 row_shr:1 row_mask:0xf bank_mask:0xf
	v_fmac_f32_dpp v238, v16, v158 row_shl:15 row_mask:0xf bank_mask:0xf
	v_fmac_f32_dpp v239, v17, v159 row_shl:15 row_mask:0xf bank_mask:0xf
	v_fmac_f32_dpp v240, v18, v160 row_shl:15 row_mask:0xf bank_mask:0xf
	v_fmac_f32_dpp v241, v19, v161 row_shl:15 row_mask:0xf bank_mask:0xf
	v_fmac_f32_dpp v238, v12, v166 row_shl:1 row_mask:0xf bank_mask:0xf
	v_fmac_f32_dpp v239, v13, v167 row_shl:1 row_mask:0xf bank_mask:0xf
	v_fmac_f32_dpp v240, v14, v168 row_shl:1 row_mask:0xf bank_mask:0xf
	v_fmac_f32_dpp v241, v15, v169 row_shl:1 row_mask:0xf bank_mask:0xf
	v_mul_f32_e32 v242, 0xbfb8aa3b, v226
	v_mul_f32_e32 v243, 0xbfb8aa3b, v227
	v_mul_f32_e32 v244, 0xbfb8aa3b, v228
	v_mul_f32_e32 v245, 0xbfb8aa3b, v229
	v_mul_f32_e32 v246, 0xbfb8aa3b, v230
	v_mul_f32_e32 v247, 0xbfb8aa3b, v231
	v_mul_f32_e32 v248, 0xbfb8aa3b, v232
	v_mul_f32_e32 v249, 0xbfb8aa3b, v233
	v_exp_f32_e32 v242, v242
	v_exp_f32_e32 v243, v243
	v_exp_f32_e32 v244, v244
	v_exp_f32_e32 v245, v245
	v_exp_f32_e32 v246, v246
	v_exp_f32_e32 v247, v247
	v_exp_f32_e32 v248, v248
	v_exp_f32_e32 v249, v249
	v_add_f32_e32 v242, 1.0, v242
	v_add_f32_e32 v243, 1.0, v243
	v_add_f32_e32 v244, 1.0, v244
	v_add_f32_e32 v245, 1.0, v245
	v_add_f32_e32 v246, 1.0, v246
	v_add_f32_e32 v247, 1.0, v247
	v_add_f32_e32 v248, 1.0, v248
	v_add_f32_e32 v249, 1.0, v249
	v_rcp_f32_e32 v242, v242
	v_rcp_f32_e32 v243, v243
	v_rcp_f32_e32 v244, v244
	v_rcp_f32_e32 v245, v245
	v_rcp_f32_e32 v246, v246
	v_rcp_f32_e32 v247, v247
	v_rcp_f32_e32 v248, v248
	v_rcp_f32_e32 v249, v249
	v_mul_f32_e32 v242, v226, v242
	v_mul_f32_e32 v243, v227, v243
	v_mul_f32_e32 v244, v228, v244
	v_mul_f32_e32 v245, v229, v245
	v_mul_f32_e32 v246, v230, v246
	v_mul_f32_e32 v247, v231, v247
	v_mul_f32_e32 v248, v232, v248
	v_mul_f32_e32 v249, v233, v249
	v_mul_f32_e32 v174, v174, v242
	v_mul_f32_e32 v175, v175, v243
	v_mul_f32_e32 v176, v176, v244
	v_mul_f32_e32 v177, v177, v245
	v_mul_f32_e32 v178, v178, v246
	v_mul_f32_e32 v179, v179, v247
	v_mul_f32_e32 v180, v180, v248
	v_mul_f32_e32 v181, v181, v249
	v_mul_f32_e32 v242, 0xbfb8aa3b, v234
	v_mul_f32_e32 v243, 0xbfb8aa3b, v235
	v_mul_f32_e32 v244, 0xbfb8aa3b, v236
	v_mul_f32_e32 v245, 0xbfb8aa3b, v237
	v_mul_f32_e32 v246, 0xbfb8aa3b, v238
	v_mul_f32_e32 v247, 0xbfb8aa3b, v239
	v_mul_f32_e32 v248, 0xbfb8aa3b, v240
	v_mul_f32_e32 v249, 0xbfb8aa3b, v241
	v_exp_f32_e32 v242, v242
	v_exp_f32_e32 v243, v243
	v_exp_f32_e32 v244, v244
	v_exp_f32_e32 v245, v245
	v_exp_f32_e32 v246, v246
	v_exp_f32_e32 v247, v247
	v_exp_f32_e32 v248, v248
	v_exp_f32_e32 v249, v249
	v_add_f32_e32 v242, 1.0, v242
	v_add_f32_e32 v243, 1.0, v243
	v_add_f32_e32 v244, 1.0, v244
	v_add_f32_e32 v245, 1.0, v245
	v_add_f32_e32 v246, 1.0, v246
	v_add_f32_e32 v247, 1.0, v247
	v_add_f32_e32 v248, 1.0, v248
	v_add_f32_e32 v249, 1.0, v249
	v_rcp_f32_e32 v242, v242
	v_rcp_f32_e32 v243, v243
	v_rcp_f32_e32 v244, v244
	v_rcp_f32_e32 v245, v245
	v_rcp_f32_e32 v246, v246
	v_rcp_f32_e32 v247, v247
	v_rcp_f32_e32 v248, v248
	v_rcp_f32_e32 v249, v249
	v_mul_f32_e32 v242, v234, v242
	v_mul_f32_e32 v243, v235, v243
	v_mul_f32_e32 v244, v236, v244
	v_mul_f32_e32 v245, v237, v245
	v_mul_f32_e32 v246, v238, v246
	v_mul_f32_e32 v247, v239, v247
	v_mul_f32_e32 v248, v240, v248
	v_mul_f32_e32 v249, v241, v249
	v_mul_f32_e32 v186, v186, v242
	v_mul_f32_e32 v187, v187, v243
	v_mul_f32_e32 v188, v188, v244
	v_mul_f32_e32 v189, v189, v245
	v_mul_f32_e32 v190, v190, v246
	v_mul_f32_e32 v191, v191, v247
	v_mul_f32_e32 v192, v192, v248
	v_mul_f32_e32 v193, v193, v249
	v_cvt_pk_bf16_f32 v46, v174, v175
	v_cvt_pk_bf16_f32 v47, v176, v177
	v_cvt_pk_bf16_f32 v62, v178, v179
	v_cvt_pk_bf16_f32 v63, v180, v181
	v_cvt_pk_bf16_f32 v58, v186, v187
	v_cvt_pk_bf16_f32 v59, v188, v189
	v_cvt_pk_bf16_f32 v42, v190, v191
	v_cvt_pk_bf16_f32 v43, v192, v193
	s_add_u32 s0, s6, 0xb0000
	s_addc_u32 s1, s7, 0
	global_store_dwordx4 v194, v[44:47], s[0:1]
	s_add_u32 s0, s6, 0xc6000
	s_addc_u32 s1, s7, 0
	global_store_dwordx4 v194, v[60:63], s[0:1]
	s_add_u32 s0, s6, 0xdc000
	s_addc_u32 s1, s7, 0
	global_store_dwordx4 v194, v[56:59], s[0:1]
	s_add_u32 s0, s6, 0xf2000
	s_addc_u32 s1, s7, 0
	global_store_dwordx4 v194, v[40:43], s[0:1]
